# attention epilogue (B l=1, C prompt, D first item): gate words and gated outputs staged through the idle K/V LDS tile so global accesses are full 512B row segments; gate loads issued before the PV loo
# speedup vs baseline: 1.0407x; 1.0015x over previous
.LBB0_370:
	s_and_b64 vcc, exec, s[0:1]
	s_barrier
	s_waitcnt vmcnt(15)
	ds_write_b128 v151, v[24:27]
	s_waitcnt vmcnt(14)
	ds_write_b128 v152, v[28:31]
	s_waitcnt vmcnt(13)
	ds_write_b128 v153, v[32:35]
	s_waitcnt vmcnt(12)
	ds_write_b128 v154, v[36:39]
	s_waitcnt vmcnt(11)
	ds_write_b128 v155, v[44:47]
	s_waitcnt vmcnt(10)
	ds_write_b128 v156, v[48:51]
	s_waitcnt vmcnt(9)
	ds_write_b128 v157, v[52:55]
	s_waitcnt vmcnt(8)
	ds_write_b128 v158, v[56:59]
	s_waitcnt vmcnt(7)
	ds_write_b128 v159, v[64:67]
	s_waitcnt vmcnt(6)
	ds_write_b128 v160, v[68:71]
	s_waitcnt vmcnt(5)
	ds_write_b128 v162, v[72:75]
	s_waitcnt vmcnt(4)
	ds_write_b128 v164, v[76:79]
	s_waitcnt vmcnt(3)
	ds_write_b128 v165, v[84:87]
	s_waitcnt vmcnt(2)
	ds_write_b128 v166, v[88:91]
	s_waitcnt vmcnt(1)
	ds_write_b128 v167, v[92:95]
	s_waitcnt vmcnt(0)
	ds_write_b128 v175, v[96:99]
	s_waitcnt lgkmcnt(0)
	s_barrier
	s_cbranch_vccnz .LBB0_372
	v_readlane_b32 s0, v235, 14
	v_readlane_b32 s1, v235, 15
	v_and_b32_e32 v182, 63, v194
	v_lshrrev_b32_e32 v183, 5, v182
	v_and_b32_e32 v184, 31, v182
	v_and_b32_e32 v185, 15, v182
	v_lshrrev_b32_e32 v186, 4, v182
	v_sub_u32_e32 v188, v183, v185
	v_mul_i32_i24_e32 v188, 0x3000, v188
	v_lshl_add_u32 v188, v184, 4, v188
	v_lshlrev_b32_e32 v189, 3, v186
	v_sub_u32_e32 v188, v188, v189
	v_ashrrev_i32_e32 v189, 31, v188
	v_lshrrev_b32_e32 v187, 6, v194
	v_mul_u32_u24_e32 v187, 0x4400, v187
	v_mul_u32_u24_e32 v201, 0x220, v183
	v_add_u32_e32 v201, v201, v187
	v_lshl_add_u32 v201, v184, 4, v201
	v_mul_u32_u24_e32 v182, 0x220, v185
	v_add_u32_e32 v187, v187, v182
	v_lshl_add_u32 v187, v186, 3, v187
	v_lshlrev_b32_e32 v192, 3, v161
	v_mov_b32_e32 v193, 0
	v_mov_b64_e32 v[190:191], s[0:1]
	v_mad_i64_i32 v[190:191], vcc, v163, s66, v[190:191]
	v_lshl_add_u64 v[190:191], v[190:191], 0, v[192:193]
	v_lshl_add_u64 v[190:191], v[190:191], 0, v[188:189]
	s_mov_b64 s[0:1], 0x6000
	s_movk_i32 vcc_lo, 0x2000
	s_mov_b32 vcc_hi, 0
	v_lshl_add_u64 v[190:191], v[190:191], 0, vcc
	global_load_dwordx4 v[202:205], v[190:191], off offset:2048
	v_lshl_add_u64 v[190:191], v[190:191], 0, s[0:1]
	global_load_dwordx4 v[206:209], v[190:191], off offset:2048
	v_lshl_add_u64 v[190:191], v[190:191], 0, s[0:1]
	global_load_dwordx4 v[210:213], v[190:191], off offset:2048
	v_lshl_add_u64 v[190:191], v[190:191], 0, s[0:1]
	global_load_dwordx4 v[214:217], v[190:191], off offset:2048
	v_lshl_add_u64 v[190:191], v[190:191], 0, s[0:1]
	global_load_dwordx4 v[218:221], v[190:191], off offset:2048
	v_lshl_add_u64 v[190:191], v[190:191], 0, s[0:1]
	global_load_dwordx4 v[222:225], v[190:191], off offset:2048
	v_lshl_add_u64 v[190:191], v[190:191], 0, s[0:1]
	global_load_dwordx4 v[226:229], v[190:191], off offset:2048
	v_lshl_add_u64 v[190:191], v[190:191], 0, s[0:1]
	global_load_dwordx4 v[230:233], v[190:191], off offset:2048
	ds_read_b128 v[0:3], v174
	ds_read_b128 v[4:7], v174 offset:8704
	ds_read_b128 v[8:11], v174 offset:17408
	ds_read_b128 v[12:15], v174 offset:26112
	ds_read_b128 v[16:19], v174 offset:34816
	ds_read_b128 v[20:23], v174 offset:43520
	ds_read_b128 v[24:27], v174 offset:52224
	ds_read_b128 v[28:31], v174 offset:60928
	v_add_u32_e32 v32, 0x11000, v172
	v_add_u32_e32 v36, 0x13200, v172
	v_add_u32_e32 v40, 0x15400, v172
	v_add_u32_e32 v44, 0x17600, v172
	v_add_u32_e32 v48, 0x19800, v172
	v_add_u32_e32 v52, 0x1ba00, v172
	v_add_u32_e32 v56, 0x1dc00, v172
	v_add_u32_e32 v60, 0x1fe00, v172
	ds_read_b128 v[32:35], v32
	ds_read_b128 v[36:39], v36
	ds_read_b128 v[40:43], v40
	ds_read_b128 v[44:47], v44
	ds_read_b128 v[48:51], v48
	ds_read_b128 v[52:55], v52
	ds_read_b128 v[56:59], v56
	ds_read_b128 v[60:63], v60
	s_waitcnt lgkmcnt(14)
	v_mfma_f32_16x16x32_bf16 v[0:3], v[0:3], v[116:119], 0
	v_mfma_f32_16x16x32_bf16 v[4:7], v[4:7], v[116:119], 0
	s_waitcnt lgkmcnt(13)
	v_mfma_f32_16x16x32_bf16 v[8:11], v[8:11], v[116:119], 0
	s_waitcnt lgkmcnt(12)
	v_mfma_f32_16x16x32_bf16 v[12:15], v[12:15], v[116:119], 0
	s_waitcnt lgkmcnt(11)
	v_mfma_f32_16x16x32_bf16 v[16:19], v[16:19], v[116:119], 0
	s_waitcnt lgkmcnt(10)
	v_mfma_f32_16x16x32_bf16 v[20:23], v[20:23], v[116:119], 0
	s_waitcnt lgkmcnt(9)
	v_mfma_f32_16x16x32_bf16 v[24:27], v[24:27], v[116:119], 0
	s_waitcnt lgkmcnt(8)
	v_mfma_f32_16x16x32_bf16 v[28:31], v[28:31], v[116:119], 0
	ds_read_b128 v[64:67], v174 offset:60992
	ds_read_b128 v[68:71], v174 offset:52288
	ds_read_b128 v[72:75], v174 offset:43584
	ds_read_b128 v[76:79], v174 offset:34880
	ds_read_b128 v[80:83], v174 offset:26176
	ds_read_b128 v[84:87], v174 offset:17472
	ds_read_b128 v[88:91], v174 offset:8768
	ds_read_b128 v[92:95], v174 offset:64
	s_waitcnt lgkmcnt(14)
	v_mfma_f32_16x16x32_bf16 v[32:35], v[32:35], v[116:119], 0
	v_mfma_f32_16x16x32_bf16 v[36:39], v[36:39], v[116:119], 0
	s_waitcnt lgkmcnt(13)
	v_mfma_f32_16x16x32_bf16 v[40:43], v[40:43], v[116:119], 0
	s_waitcnt lgkmcnt(12)
	v_mfma_f32_16x16x32_bf16 v[44:47], v[44:47], v[116:119], 0
	s_waitcnt lgkmcnt(11)
	v_mfma_f32_16x16x32_bf16 v[48:51], v[48:51], v[116:119], 0
	s_waitcnt lgkmcnt(10)
	v_mfma_f32_16x16x32_bf16 v[52:55], v[52:55], v[116:119], 0
	s_waitcnt lgkmcnt(9)
	v_mfma_f32_16x16x32_bf16 v[56:59], v[56:59], v[116:119], 0
	s_waitcnt lgkmcnt(8)
	v_mfma_f32_16x16x32_bf16 v[60:63], v[60:63], v[116:119], 0
	v_add_u32_e32 v96, 0x11040, v172
	v_add_u32_e32 v100, 0x13240, v172
	v_add_u32_e32 v116, 0x15440, v172
	v_add_u32_e32 v124, 0x17640, v172
	ds_read_b128 v[96:99], v96
	ds_read_b128 v[100:103], v100
	ds_read_b128 v[116:119], v116
	ds_read_b128 v[134:137], v124
	v_add_u32_e32 v124, 0x19840, v172
	v_add_u32_e32 v125, 0x1ba40, v172
	ds_read_b128 v[144:147], v124
	ds_read_b128 v[152:155], v125
	v_add_u32_e32 v124, 0x1dc40, v172
	v_add_u32_e32 v125, 0x1fe40, v172
	ds_read_b128 v[156:159], v124
	ds_read_b128 v[164:167], v125
	s_waitcnt lgkmcnt(8)
	v_mfma_f32_16x16x32_bf16 v[0:3], v[92:95], v[104:107], v[0:3]
	v_mfma_f32_16x16x32_bf16 v[4:7], v[88:91], v[104:107], v[4:7]
	v_mfma_f32_16x16x32_bf16 v[8:11], v[84:87], v[104:107], v[8:11]
	v_mfma_f32_16x16x32_bf16 v[12:15], v[80:83], v[104:107], v[12:15]
	v_mfma_f32_16x16x32_bf16 v[16:19], v[76:79], v[104:107], v[16:19]
	v_mfma_f32_16x16x32_bf16 v[20:23], v[72:75], v[104:107], v[20:23]
	v_mfma_f32_16x16x32_bf16 v[24:27], v[68:71], v[104:107], v[24:27]
	v_mfma_f32_16x16x32_bf16 v[28:31], v[64:67], v[104:107], v[28:31]
	ds_read_b128 v[64:67], v174 offset:61056
	ds_read_b128 v[68:71], v174 offset:52352
	ds_read_b128 v[72:75], v174 offset:43648
	ds_read_b128 v[76:79], v174 offset:34944
	ds_read_b128 v[80:83], v174 offset:26240
	ds_read_b128 v[84:87], v174 offset:17536
	ds_read_b128 v[88:91], v174 offset:8832
	ds_read_b128 v[92:95], v174 offset:128
	s_waitcnt lgkmcnt(14)
	v_mfma_f32_16x16x32_bf16 v[32:35], v[96:99], v[104:107], v[32:35]
	v_mfma_f32_16x16x32_bf16 v[36:39], v[100:103], v[104:107], v[36:39]
	s_waitcnt lgkmcnt(13)
	v_mfma_f32_16x16x32_bf16 v[40:43], v[116:119], v[104:107], v[40:43]
	s_waitcnt lgkmcnt(12)
	v_mfma_f32_16x16x32_bf16 v[44:47], v[134:137], v[104:107], v[44:47]
	s_waitcnt lgkmcnt(11)
	v_mfma_f32_16x16x32_bf16 v[48:51], v[144:147], v[104:107], v[48:51]
	s_waitcnt lgkmcnt(10)
	v_mfma_f32_16x16x32_bf16 v[52:55], v[152:155], v[104:107], v[52:55]
	s_waitcnt lgkmcnt(9)
	v_mfma_f32_16x16x32_bf16 v[56:59], v[156:159], v[104:107], v[56:59]
	s_waitcnt lgkmcnt(8)
	v_mfma_f32_16x16x32_bf16 v[60:63], v[164:167], v[104:107], v[60:63]
	v_add_u32_e32 v96, 0x11080, v172
	v_add_u32_e32 v100, 0x13280, v172
	v_add_u32_e32 v104, 0x15480, v172
	v_add_u32_e32 v116, 0x17680, v172
	v_add_u32_e32 v124, 0x19880, v172
	ds_read_b128 v[96:99], v96
	ds_read_b128 v[100:103], v100
	ds_read_b128 v[104:107], v104
	ds_read_b128 v[116:119], v116
	v_add_u32_e32 v125, 0x1ba80, v172
	ds_read_b128 v[134:137], v124
	ds_read_b128 v[144:147], v125
	v_add_u32_e32 v124, 0x1dc80, v172
	v_add_u32_e32 v125, 0x1fe80, v172
	ds_read_b128 v[152:155], v124
	ds_read_b128 v[156:159], v125
	s_waitcnt lgkmcnt(8)
	v_mfma_f32_16x16x32_bf16 v[0:3], v[92:95], v[112:115], v[0:3]
	v_mfma_f32_16x16x32_bf16 v[4:7], v[88:91], v[112:115], v[4:7]
	v_mfma_f32_16x16x32_bf16 v[8:11], v[84:87], v[112:115], v[8:11]
	v_mfma_f32_16x16x32_bf16 v[12:15], v[80:83], v[112:115], v[12:15]
	v_mfma_f32_16x16x32_bf16 v[16:19], v[76:79], v[112:115], v[16:19]
	v_mfma_f32_16x16x32_bf16 v[20:23], v[72:75], v[112:115], v[20:23]
	v_mfma_f32_16x16x32_bf16 v[24:27], v[68:71], v[112:115], v[24:27]
	v_mfma_f32_16x16x32_bf16 v[28:31], v[64:67], v[112:115], v[28:31]
	ds_read_b128 v[64:67], v174 offset:61120
	ds_read_b128 v[68:71], v174 offset:52416
	ds_read_b128 v[72:75], v174 offset:43712
	ds_read_b128 v[76:79], v174 offset:35008
	ds_read_b128 v[80:83], v174 offset:26304
	ds_read_b128 v[84:87], v174 offset:17600
	ds_read_b128 v[88:91], v174 offset:8896
	ds_read_b128 v[92:95], v174 offset:192
	s_waitcnt lgkmcnt(14)
	v_mfma_f32_16x16x32_bf16 v[32:35], v[96:99], v[112:115], v[32:35]
	v_mfma_f32_16x16x32_bf16 v[36:39], v[100:103], v[112:115], v[36:39]
	s_waitcnt lgkmcnt(13)
	v_mfma_f32_16x16x32_bf16 v[40:43], v[104:107], v[112:115], v[40:43]
	s_waitcnt lgkmcnt(12)
	v_mfma_f32_16x16x32_bf16 v[44:47], v[116:119], v[112:115], v[44:47]
	s_waitcnt lgkmcnt(11)
	v_mfma_f32_16x16x32_bf16 v[48:51], v[134:137], v[112:115], v[48:51]
	s_waitcnt lgkmcnt(10)
	v_mfma_f32_16x16x32_bf16 v[52:55], v[144:147], v[112:115], v[52:55]
	s_waitcnt lgkmcnt(9)
	v_mfma_f32_16x16x32_bf16 v[56:59], v[152:155], v[112:115], v[56:59]
	s_waitcnt lgkmcnt(8)
	v_mfma_f32_16x16x32_bf16 v[60:63], v[156:159], v[112:115], v[60:63]
	v_add_u32_e32 v96, 0x110c0, v172
	v_add_u32_e32 v100, 0x132c0, v172
	v_add_u32_e32 v104, 0x154c0, v172
	v_add_u32_e32 v112, 0x176c0, v172
	v_add_u32_e32 v116, 0x198c0, v172
	v_add_u32_e32 v124, 0x1bac0, v172
	ds_read_b128 v[96:99], v96
	ds_read_b128 v[100:103], v100
	ds_read_b128 v[104:107], v104
	ds_read_b128 v[112:115], v112
	ds_read_b128 v[116:119], v116
	ds_read_b128 v[134:137], v124
	v_add_u32_e32 v124, 0x1dcc0, v172
	v_add_u32_e32 v125, 0x1fec0, v172
	ds_read_b128 v[144:147], v124
	ds_read_b128 v[152:155], v125
	s_waitcnt lgkmcnt(8)
	v_mfma_f32_16x16x32_bf16 v[0:3], v[92:95], v[120:123], v[0:3]
	v_mfma_f32_16x16x32_bf16 v[4:7], v[88:91], v[120:123], v[4:7]
	v_mfma_f32_16x16x32_bf16 v[8:11], v[84:87], v[120:123], v[8:11]
	v_mfma_f32_16x16x32_bf16 v[12:15], v[80:83], v[120:123], v[12:15]
	v_mfma_f32_16x16x32_bf16 v[16:19], v[76:79], v[120:123], v[16:19]
	v_mfma_f32_16x16x32_bf16 v[20:23], v[72:75], v[120:123], v[20:23]
	v_mfma_f32_16x16x32_bf16 v[24:27], v[68:71], v[120:123], v[24:27]
	v_mfma_f32_16x16x32_bf16 v[28:31], v[64:67], v[120:123], v[28:31]
	ds_read_b128 v[64:67], v174 offset:61184
	ds_read_b128 v[68:71], v174 offset:52480
	ds_read_b128 v[72:75], v174 offset:43776
	ds_read_b128 v[76:79], v174 offset:35072
	ds_read_b128 v[80:83], v174 offset:26368
	ds_read_b128 v[84:87], v174 offset:17664
	ds_read_b128 v[88:91], v174 offset:8960
	ds_read_b128 v[92:95], v174 offset:256
	s_waitcnt lgkmcnt(14)
	v_mfma_f32_16x16x32_bf16 v[32:35], v[96:99], v[120:123], v[32:35]
	v_mfma_f32_16x16x32_bf16 v[36:39], v[100:103], v[120:123], v[36:39]
	s_waitcnt lgkmcnt(13)
	v_mfma_f32_16x16x32_bf16 v[40:43], v[104:107], v[120:123], v[40:43]
	s_waitcnt lgkmcnt(12)
	v_mfma_f32_16x16x32_bf16 v[44:47], v[112:115], v[120:123], v[44:47]
	s_waitcnt lgkmcnt(11)
	v_mfma_f32_16x16x32_bf16 v[48:51], v[116:119], v[120:123], v[48:51]
	s_waitcnt lgkmcnt(10)
	v_mfma_f32_16x16x32_bf16 v[52:55], v[134:137], v[120:123], v[52:55]
	s_waitcnt lgkmcnt(9)
	v_mfma_f32_16x16x32_bf16 v[56:59], v[144:147], v[120:123], v[56:59]
	s_waitcnt lgkmcnt(8)
	v_mfma_f32_16x16x32_bf16 v[60:63], v[152:155], v[120:123], v[60:63]
	v_add_u32_e32 v96, 0x11100, v172
	v_add_u32_e32 v100, 0x13300, v172
	v_add_u32_e32 v104, 0x15500, v172
	v_add_u32_e32 v112, 0x17700, v172
	v_add_u32_e32 v116, 0x19900, v172
	v_add_u32_e32 v120, 0x1bb00, v172
	v_add_u32_e32 v124, 0x1dd00, v172
	ds_read_b128 v[96:99], v96
	ds_read_b128 v[100:103], v100
	ds_read_b128 v[104:107], v104
	ds_read_b128 v[112:115], v112
	ds_read_b128 v[116:119], v116
	ds_read_b128 v[120:123], v120
	v_add_u32_e32 v125, 0x1ff00, v172
	ds_read_b128 v[134:137], v124
	ds_read_b128 v[144:147], v125
	s_waitcnt lgkmcnt(8)
	v_mfma_f32_16x16x32_bf16 v[0:3], v[92:95], v[108:111], v[0:3]
	v_mfma_f32_16x16x32_bf16 v[4:7], v[88:91], v[108:111], v[4:7]
	v_mfma_f32_16x16x32_bf16 v[8:11], v[84:87], v[108:111], v[8:11]
	v_mfma_f32_16x16x32_bf16 v[12:15], v[80:83], v[108:111], v[12:15]
	v_mfma_f32_16x16x32_bf16 v[16:19], v[76:79], v[108:111], v[16:19]
	v_mfma_f32_16x16x32_bf16 v[20:23], v[72:75], v[108:111], v[20:23]
	v_mfma_f32_16x16x32_bf16 v[24:27], v[68:71], v[108:111], v[24:27]
	v_mfma_f32_16x16x32_bf16 v[28:31], v[64:67], v[108:111], v[28:31]
	ds_read_b128 v[64:67], v174 offset:61248
	ds_read_b128 v[68:71], v174 offset:52544
	ds_read_b128 v[72:75], v174 offset:43840
	ds_read_b128 v[76:79], v174 offset:35136
	ds_read_b128 v[80:83], v174 offset:26432
	ds_read_b128 v[84:87], v174 offset:17728
	ds_read_b128 v[88:91], v174 offset:9024
	ds_read_b128 v[92:95], v174 offset:320
	s_waitcnt lgkmcnt(14)
	v_mfma_f32_16x16x32_bf16 v[32:35], v[96:99], v[108:111], v[32:35]
	v_mfma_f32_16x16x32_bf16 v[36:39], v[100:103], v[108:111], v[36:39]
	s_waitcnt lgkmcnt(13)
	v_mfma_f32_16x16x32_bf16 v[40:43], v[104:107], v[108:111], v[40:43]
	s_waitcnt lgkmcnt(12)
	v_mfma_f32_16x16x32_bf16 v[44:47], v[112:115], v[108:111], v[44:47]
	s_waitcnt lgkmcnt(11)
	v_mfma_f32_16x16x32_bf16 v[48:51], v[116:119], v[108:111], v[48:51]
	s_waitcnt lgkmcnt(10)
	v_mfma_f32_16x16x32_bf16 v[52:55], v[120:123], v[108:111], v[52:55]
	s_waitcnt lgkmcnt(9)
	v_mfma_f32_16x16x32_bf16 v[56:59], v[134:137], v[108:111], v[56:59]
	s_waitcnt lgkmcnt(8)
	v_mfma_f32_16x16x32_bf16 v[60:63], v[144:147], v[108:111], v[60:63]
	v_add_u32_e32 v96, 0x11140, v172
	v_add_u32_e32 v100, 0x13340, v172
	v_add_u32_e32 v104, 0x15540, v172
	v_add_u32_e32 v108, 0x17740, v172
	v_add_u32_e32 v112, 0x19940, v172
	v_add_u32_e32 v116, 0x1bb40, v172
	v_add_u32_e32 v120, 0x1dd40, v172
	ds_read_b128 v[96:99], v96
	ds_read_b128 v[100:103], v100
	ds_read_b128 v[104:107], v104
	ds_read_b128 v[108:111], v108
	ds_read_b128 v[112:115], v112
	ds_read_b128 v[116:119], v116
	v_add_u32_e32 v124, 0x1ff40, v172
	ds_read_b128 v[120:123], v120
	ds_read_b128 v[134:137], v124
	s_waitcnt lgkmcnt(8)
	v_mfma_f32_16x16x32_bf16 v[0:3], v[92:95], v[130:133], v[0:3]
	v_mfma_f32_16x16x32_bf16 v[4:7], v[88:91], v[130:133], v[4:7]
	v_mfma_f32_16x16x32_bf16 v[8:11], v[84:87], v[130:133], v[8:11]
	v_mfma_f32_16x16x32_bf16 v[12:15], v[80:83], v[130:133], v[12:15]
	v_mfma_f32_16x16x32_bf16 v[16:19], v[76:79], v[130:133], v[16:19]
	v_mfma_f32_16x16x32_bf16 v[20:23], v[72:75], v[130:133], v[20:23]
	v_mfma_f32_16x16x32_bf16 v[24:27], v[68:71], v[130:133], v[24:27]
	v_mfma_f32_16x16x32_bf16 v[28:31], v[64:67], v[130:133], v[28:31]
	ds_read_b128 v[64:67], v174 offset:61312
	ds_read_b128 v[68:71], v174 offset:52608
	ds_read_b128 v[72:75], v174 offset:43904
	ds_read_b128 v[76:79], v174 offset:35200
	ds_read_b128 v[80:83], v174 offset:26496
	ds_read_b128 v[84:87], v174 offset:17792
	ds_read_b128 v[88:91], v174 offset:9088
	ds_read_b128 v[92:95], v174 offset:384
	s_waitcnt lgkmcnt(14)
	v_mfma_f32_16x16x32_bf16 v[32:35], v[96:99], v[130:133], v[32:35]
	v_mfma_f32_16x16x32_bf16 v[36:39], v[100:103], v[130:133], v[36:39]
	s_waitcnt lgkmcnt(13)
	v_mfma_f32_16x16x32_bf16 v[40:43], v[104:107], v[130:133], v[40:43]
	s_waitcnt lgkmcnt(12)
	v_mfma_f32_16x16x32_bf16 v[44:47], v[108:111], v[130:133], v[44:47]
	s_waitcnt lgkmcnt(11)
	v_mfma_f32_16x16x32_bf16 v[48:51], v[112:115], v[130:133], v[48:51]
	s_waitcnt lgkmcnt(10)
	v_mfma_f32_16x16x32_bf16 v[52:55], v[116:119], v[130:133], v[52:55]
	s_waitcnt lgkmcnt(9)
	v_mfma_f32_16x16x32_bf16 v[56:59], v[120:123], v[130:133], v[56:59]
	s_waitcnt lgkmcnt(8)
	v_mfma_f32_16x16x32_bf16 v[60:63], v[134:137], v[130:133], v[60:63]
	v_add_u32_e32 v96, 0x11180, v172
	v_add_u32_e32 v100, 0x13380, v172
	v_add_u32_e32 v104, 0x15580, v172
	v_add_u32_e32 v108, 0x17780, v172
	v_add_u32_e32 v112, 0x19980, v172
	v_add_u32_e32 v116, 0x1bb80, v172
	v_add_u32_e32 v120, 0x1dd80, v172
	ds_read_b128 v[96:99], v96
	ds_read_b128 v[100:103], v100
	ds_read_b128 v[104:107], v104
	ds_read_b128 v[108:111], v108
	ds_read_b128 v[112:115], v112
	ds_read_b128 v[116:119], v116
	v_add_u32_e32 v124, 0x1ff80, v172
	ds_read_b128 v[120:123], v120
	ds_read_b128 v[130:133], v124
	s_waitcnt lgkmcnt(8)
	v_mfma_f32_16x16x32_bf16 v[0:3], v[92:95], v[140:143], v[0:3]
	v_mfma_f32_16x16x32_bf16 v[4:7], v[88:91], v[140:143], v[4:7]
	v_mfma_f32_16x16x32_bf16 v[8:11], v[84:87], v[140:143], v[8:11]
	v_mfma_f32_16x16x32_bf16 v[12:15], v[80:83], v[140:143], v[12:15]
	v_mfma_f32_16x16x32_bf16 v[16:19], v[76:79], v[140:143], v[16:19]
	v_mfma_f32_16x16x32_bf16 v[20:23], v[72:75], v[140:143], v[20:23]
	v_mfma_f32_16x16x32_bf16 v[24:27], v[68:71], v[140:143], v[24:27]
	v_mfma_f32_16x16x32_bf16 v[28:31], v[64:67], v[140:143], v[28:31]
	ds_read_b128 v[64:67], v174 offset:61376
	ds_read_b128 v[68:71], v174 offset:52672
	ds_read_b128 v[72:75], v174 offset:43968
	ds_read_b128 v[76:79], v174 offset:35264
	ds_read_b128 v[80:83], v174 offset:26560
	ds_read_b128 v[84:87], v174 offset:17856
	ds_read_b128 v[88:91], v174 offset:9152
	ds_read_b128 v[92:95], v174 offset:448
	s_waitcnt lgkmcnt(14)
	v_mfma_f32_16x16x32_bf16 v[96:99], v[96:99], v[140:143], v[32:35]
	v_mfma_f32_16x16x32_bf16 v[100:103], v[100:103], v[140:143], v[36:39]
	s_waitcnt lgkmcnt(13)
	v_mfma_f32_16x16x32_bf16 v[104:107], v[104:107], v[140:143], v[40:43]
	s_waitcnt lgkmcnt(12)
	v_mfma_f32_16x16x32_bf16 v[108:111], v[108:111], v[140:143], v[44:47]
	s_waitcnt lgkmcnt(11)
	v_mfma_f32_16x16x32_bf16 v[112:115], v[112:115], v[140:143], v[48:51]
	s_waitcnt lgkmcnt(10)
	v_mfma_f32_16x16x32_bf16 v[116:119], v[116:119], v[140:143], v[52:55]
	s_waitcnt lgkmcnt(9)
	v_mfma_f32_16x16x32_bf16 v[120:123], v[120:123], v[140:143], v[56:59]
	s_waitcnt lgkmcnt(8)
	v_mfma_f32_16x16x32_bf16 v[130:133], v[130:133], v[140:143], v[60:63]
	v_add_u32_e32 v32, 0x111c0, v172
	v_add_u32_e32 v33, 0x133c0, v172
	ds_read_b128 v[134:137], v32
	ds_read_b128 v[138:141], v33
	v_add_u32_e32 v32, 0x155c0, v172
	v_add_u32_e32 v33, 0x177c0, v172
	ds_read_b128 v[142:145], v32
	ds_read_b128 v[146:149], v33
	v_add_u32_e32 v32, 0x199c0, v172
	v_add_u32_e32 v33, 0x1bbc0, v172
	ds_read_b128 v[152:155], v32
	ds_read_b128 v[156:159], v33
	v_add_u32_e32 v32, 0x1ddc0, v172
	v_add_u32_e32 v33, 0x1ffc0, v172
	ds_read_b128 v[164:167], v32
	ds_read_b128 v[174:177], v33
	s_waitcnt lgkmcnt(8)
	v_mfma_f32_16x16x32_bf16 v[60:63], v[92:95], v[126:129], v[0:3]
	v_mfma_f32_16x16x32_bf16 v[56:59], v[88:91], v[126:129], v[4:7]
	v_mfma_f32_16x16x32_bf16 v[52:55], v[84:87], v[126:129], v[8:11]
	v_mfma_f32_16x16x32_bf16 v[48:51], v[80:83], v[126:129], v[12:15]
	v_mfma_f32_16x16x32_bf16 v[44:47], v[76:79], v[126:129], v[16:19]
	v_mfma_f32_16x16x32_bf16 v[40:43], v[72:75], v[126:129], v[20:23]
	v_mfma_f32_16x16x32_bf16 v[36:39], v[68:71], v[126:129], v[24:27]
	v_mfma_f32_16x16x32_bf16 v[32:35], v[64:67], v[126:129], v[28:31]
	s_waitcnt lgkmcnt(7)
	v_mfma_f32_16x16x32_bf16 v[28:31], v[134:137], v[126:129], v[96:99]
	s_waitcnt lgkmcnt(6)
	v_mfma_f32_16x16x32_bf16 v[24:27], v[138:141], v[126:129], v[100:103]
	s_waitcnt lgkmcnt(5)
	v_mfma_f32_16x16x32_bf16 v[20:23], v[142:145], v[126:129], v[104:107]
	s_waitcnt lgkmcnt(4)
	v_mfma_f32_16x16x32_bf16 v[16:19], v[146:149], v[126:129], v[108:111]
	s_waitcnt lgkmcnt(3)
	v_mfma_f32_16x16x32_bf16 v[12:15], v[152:155], v[126:129], v[112:115]
	s_waitcnt lgkmcnt(2)
	v_mfma_f32_16x16x32_bf16 v[8:11], v[156:159], v[126:129], v[116:119]
	s_waitcnt lgkmcnt(1)
	v_mfma_f32_16x16x32_bf16 v[4:7], v[164:167], v[126:129], v[120:123]
	s_waitcnt lgkmcnt(0)
	v_mfma_f32_16x16x32_bf16 v[0:3], v[174:177], v[126:129], v[130:133]
	v_readlane_b32 s0, v235, 14
	v_readlane_b32 s1, v235, 15
	v_lshlrev_b32_e32 v172, 3, v161
	s_nop 0
	v_mov_b64_e32 v[64:65], s[0:1]
	v_mad_i64_i32 v[64:65], s[0:1], v163, s66, v[64:65]
	v_lshl_add_u64 v[94:95], v[64:65], 0, v[172:173]
	v_add_co_u32_e32 v64, vcc, s92, v94
	s_nop 1
	v_addc_co_u32_e32 v65, vcc, 0, v95, vcc
	s_barrier
	s_mov_b64 s[0:1], 0x6000
	s_waitcnt vmcnt(7)
	ds_write_b128 v201, v[202:205]
	s_waitcnt vmcnt(6)
	ds_write_b128 v201, v[206:209] offset:1088
	s_waitcnt vmcnt(5)
	ds_write_b128 v201, v[210:213] offset:2176
	s_waitcnt vmcnt(4)
	ds_write_b128 v201, v[214:217] offset:3264
	s_waitcnt vmcnt(3)
	ds_write_b128 v201, v[218:221] offset:4352
	s_waitcnt vmcnt(2)
	ds_write_b128 v201, v[222:225] offset:5440
	s_waitcnt vmcnt(1)
	ds_write_b128 v201, v[226:229] offset:6528
	s_waitcnt vmcnt(0)
	ds_write_b128 v201, v[230:233] offset:7616
	ds_read_b64 v[96:97], v187
	ds_read_b64 v[92:93], v187 offset:32
	ds_read_b64 v[90:91], v187 offset:64
	ds_read_b64 v[88:89], v187 offset:96
	ds_read_b64 v[86:87], v187 offset:128
	ds_read_b64 v[84:85], v187 offset:160
	ds_read_b64 v[82:83], v187 offset:192
	ds_read_b64 v[80:81], v187 offset:224
	ds_read_b64 v[78:79], v187 offset:256
	ds_read_b64 v[76:77], v187 offset:288
	ds_read_b64 v[74:75], v187 offset:320
	ds_read_b64 v[72:73], v187 offset:352
	ds_read_b64 v[70:71], v187 offset:384
	ds_read_b64 v[68:69], v187 offset:416
	ds_read_b64 v[66:67], v187 offset:448
	ds_read_b64 v[64:65], v187 offset:480
	s_waitcnt lgkmcnt(0)
	s_waitcnt vmcnt(15)
	v_lshlrev_b32_e32 v99, 16, v96
	v_mul_f32_e32 v98, 0xbfb8aa3b, v99
	v_exp_f32_e32 v98, v98
	s_nop 0
	v_add_f32_e32 v98, 1.0, v98
	v_rcp_f32_e32 v151, v98
	v_mov_b32_e32 v98, v60
	v_pk_mul_f32 v[98:99], v[150:151], v[98:99]
	s_nop 0
	v_mul_f32_e32 v100, v98, v99
	v_and_b32_e32 v99, 0xffff0000, v96
	v_mul_f32_e32 v60, 0xbfb8aa3b, v99
	v_exp_f32_e32 v60, v60
	v_mov_b32_e32 v98, v61
	v_add_f32_e32 v60, 1.0, v60
	v_rcp_f32_e32 v151, v60
	s_nop 0
	v_pk_mul_f32 v[60:61], v[150:151], v[98:99]
	s_nop 0
	v_mul_f32_e32 v60, v60, v61
	v_lshlrev_b32_e32 v61, 16, v97
	v_cvt_pk_bf16_f32 v96, v100, v60
	v_mul_f32_e32 v60, 0xbfb8aa3b, v61
	v_exp_f32_e32 v60, v60
	s_nop 0
	v_add_f32_e32 v60, 1.0, v60
	v_rcp_f32_e32 v151, v60
	v_mov_b32_e32 v60, v62
	v_pk_mul_f32 v[60:61], v[150:151], v[60:61]
	s_nop 0
	v_mul_f32_e32 v62, v60, v61
	v_and_b32_e32 v61, 0xffff0000, v97
	v_mul_f32_e32 v60, 0xbfb8aa3b, v61
	v_exp_f32_e32 v60, v60
	s_nop 0
	v_add_f32_e32 v60, 1.0, v60
	v_rcp_f32_e32 v151, v60
	v_mov_b32_e32 v60, v63
	s_waitcnt vmcnt(14)
	v_lshlrev_b32_e32 v63, 16, v92
	v_pk_mul_f32 v[60:61], v[150:151], v[60:61]
	s_nop 0
	v_mul_f32_e32 v60, v60, v61
	v_cvt_pk_bf16_f32 v97, v62, v60
	v_mul_f32_e32 v62, 0xbfb8aa3b, v63
	v_exp_f32_e32 v62, v62
	v_add_co_u32_e32 v60, vcc, s93, v94
	v_add_f32_e32 v62, 1.0, v62
	v_rcp_f32_e32 v151, v62
	v_mov_b32_e32 v62, v56
	v_addc_co_u32_e32 v61, vcc, 0, v95, vcc
	v_pk_mul_f32 v[62:63], v[150:151], v[62:63]
	ds_write_b64 v187, v[96:97]
	v_mul_f32_e32 v94, v62, v63
	v_and_b32_e32 v63, 0xffff0000, v92
	v_mul_f32_e32 v56, 0xbfb8aa3b, v63
	v_exp_f32_e32 v56, v56
	v_mov_b32_e32 v62, v57
	v_add_f32_e32 v56, 1.0, v56
	v_rcp_f32_e32 v151, v56
	s_nop 0
	v_pk_mul_f32 v[56:57], v[150:151], v[62:63]
	v_lshlrev_b32_e32 v63, 16, v93
	v_mul_f32_e32 v56, v56, v57
	v_mul_f32_e32 v57, 0xbfb8aa3b, v63
	v_exp_f32_e32 v57, v57
	v_mov_b32_e32 v62, v58
	v_cvt_pk_bf16_f32 v56, v94, v56
	v_add_f32_e32 v57, 1.0, v57
	v_rcp_f32_e32 v151, v57
	s_nop 0
	v_pk_mul_f32 v[62:63], v[150:151], v[62:63]
	s_nop 0
	v_mul_f32_e32 v57, v62, v63
	v_and_b32_e32 v63, 0xffff0000, v93
	v_mul_f32_e32 v58, 0xbfb8aa3b, v63
	v_exp_f32_e32 v58, v58
	v_mov_b32_e32 v62, v59
	v_add_f32_e32 v58, 1.0, v58
	v_rcp_f32_e32 v151, v58
	s_nop 0
	v_pk_mul_f32 v[58:59], v[150:151], v[62:63]
	s_nop 0
	v_mul_f32_e32 v58, v58, v59
	v_cvt_pk_bf16_f32 v57, v57, v58
	ds_write_b64 v187, v[56:57] offset:32
	s_waitcnt vmcnt(15)
	v_lshlrev_b32_e32 v57, 16, v90
	v_mul_f32_e32 v56, 0xbfb8aa3b, v57
	v_exp_f32_e32 v56, v56
	s_nop 0
	v_add_f32_e32 v56, 1.0, v56
	v_rcp_f32_e32 v151, v56
	v_mov_b32_e32 v56, v52
	v_pk_mul_f32 v[56:57], v[150:151], v[56:57]
	s_nop 0
	v_mul_f32_e32 v58, v56, v57
	v_and_b32_e32 v57, 0xffff0000, v90
	v_mul_f32_e32 v52, 0xbfb8aa3b, v57
	v_exp_f32_e32 v52, v52
	v_mov_b32_e32 v56, v53
	v_add_f32_e32 v52, 1.0, v52
	v_rcp_f32_e32 v151, v52
	s_nop 0
	v_pk_mul_f32 v[52:53], v[150:151], v[56:57]
	v_lshlrev_b32_e32 v57, 16, v91
	v_mul_f32_e32 v52, v52, v53
	v_mul_f32_e32 v53, 0xbfb8aa3b, v57
	v_exp_f32_e32 v53, v53
	v_mov_b32_e32 v56, v54
	v_cvt_pk_bf16_f32 v52, v58, v52
	v_add_f32_e32 v53, 1.0, v53
	v_rcp_f32_e32 v151, v53
	s_nop 0
	v_pk_mul_f32 v[56:57], v[150:151], v[56:57]
	s_nop 0
	v_mul_f32_e32 v53, v56, v57
	v_and_b32_e32 v57, 0xffff0000, v91
	v_mul_f32_e32 v54, 0xbfb8aa3b, v57
	v_exp_f32_e32 v54, v54
	v_mov_b32_e32 v56, v55
	v_add_f32_e32 v54, 1.0, v54
	v_rcp_f32_e32 v151, v54
	s_nop 0
	v_pk_mul_f32 v[54:55], v[150:151], v[56:57]
	s_nop 0
	v_mul_f32_e32 v54, v54, v55
	v_cvt_pk_bf16_f32 v53, v53, v54
	ds_write_b64 v187, v[52:53] offset:64
	s_waitcnt vmcnt(15)
	v_lshlrev_b32_e32 v53, 16, v88
	v_mul_f32_e32 v52, 0xbfb8aa3b, v53
	v_exp_f32_e32 v52, v52
	s_nop 0
	v_add_f32_e32 v52, 1.0, v52
	v_rcp_f32_e32 v151, v52
	v_mov_b32_e32 v52, v48
	v_pk_mul_f32 v[52:53], v[150:151], v[52:53]
	s_nop 0
	v_mul_f32_e32 v54, v52, v53
	v_and_b32_e32 v53, 0xffff0000, v88
	v_mul_f32_e32 v48, 0xbfb8aa3b, v53
	v_exp_f32_e32 v48, v48
	v_mov_b32_e32 v52, v49
	v_add_f32_e32 v48, 1.0, v48
	v_rcp_f32_e32 v151, v48
	s_nop 0
	v_pk_mul_f32 v[48:49], v[150:151], v[52:53]
	v_lshlrev_b32_e32 v53, 16, v89
	v_mul_f32_e32 v48, v48, v49
	v_mul_f32_e32 v49, 0xbfb8aa3b, v53
	v_exp_f32_e32 v49, v49
	v_mov_b32_e32 v52, v50
	v_cvt_pk_bf16_f32 v48, v54, v48
	v_add_f32_e32 v49, 1.0, v49
	v_rcp_f32_e32 v151, v49
	s_nop 0
	v_pk_mul_f32 v[52:53], v[150:151], v[52:53]
	s_nop 0
	v_mul_f32_e32 v49, v52, v53
	v_and_b32_e32 v53, 0xffff0000, v89
	v_mul_f32_e32 v50, 0xbfb8aa3b, v53
	v_exp_f32_e32 v50, v50
	v_mov_b32_e32 v52, v51
	v_add_f32_e32 v50, 1.0, v50
	v_rcp_f32_e32 v151, v50
	s_nop 0
	v_pk_mul_f32 v[50:51], v[150:151], v[52:53]
	s_nop 0
	v_mul_f32_e32 v50, v50, v51
	v_cvt_pk_bf16_f32 v49, v49, v50
	ds_write_b64 v187, v[48:49] offset:96
	s_waitcnt vmcnt(15)
	v_lshlrev_b32_e32 v49, 16, v86
	v_mul_f32_e32 v48, 0xbfb8aa3b, v49
	v_exp_f32_e32 v48, v48
	s_nop 0
	v_add_f32_e32 v48, 1.0, v48
	v_rcp_f32_e32 v151, v48
	v_mov_b32_e32 v48, v44
	v_pk_mul_f32 v[48:49], v[150:151], v[48:49]
	s_nop 0
	v_mul_f32_e32 v50, v48, v49
	v_and_b32_e32 v49, 0xffff0000, v86
	v_mul_f32_e32 v44, 0xbfb8aa3b, v49
	v_exp_f32_e32 v44, v44
	v_mov_b32_e32 v48, v45
	v_add_f32_e32 v44, 1.0, v44
	v_rcp_f32_e32 v151, v44
	s_nop 0
	v_pk_mul_f32 v[44:45], v[150:151], v[48:49]
	v_lshlrev_b32_e32 v49, 16, v87
	v_mul_f32_e32 v44, v44, v45
	v_mul_f32_e32 v45, 0xbfb8aa3b, v49
	v_exp_f32_e32 v45, v45
	v_mov_b32_e32 v48, v46
	v_cvt_pk_bf16_f32 v44, v50, v44
	v_add_f32_e32 v45, 1.0, v45
	v_rcp_f32_e32 v151, v45
	s_nop 0
	v_pk_mul_f32 v[48:49], v[150:151], v[48:49]
	s_nop 0
	v_mul_f32_e32 v45, v48, v49
	v_and_b32_e32 v49, 0xffff0000, v87
	v_mul_f32_e32 v46, 0xbfb8aa3b, v49
	v_exp_f32_e32 v46, v46
	v_mov_b32_e32 v48, v47
	v_add_f32_e32 v46, 1.0, v46
	v_rcp_f32_e32 v151, v46
	s_nop 0
	v_pk_mul_f32 v[46:47], v[150:151], v[48:49]
	s_nop 0
	v_mul_f32_e32 v46, v46, v47
	v_cvt_pk_bf16_f32 v45, v45, v46
	ds_write_b64 v187, v[44:45] offset:128
	s_waitcnt vmcnt(15)
	v_lshlrev_b32_e32 v45, 16, v84
	v_mul_f32_e32 v44, 0xbfb8aa3b, v45
	v_exp_f32_e32 v44, v44
	s_nop 0
	v_add_f32_e32 v44, 1.0, v44
	v_rcp_f32_e32 v151, v44
	v_mov_b32_e32 v44, v40
	v_pk_mul_f32 v[44:45], v[150:151], v[44:45]
	s_nop 0
	v_mul_f32_e32 v46, v44, v45
	v_and_b32_e32 v45, 0xffff0000, v84
	v_mul_f32_e32 v40, 0xbfb8aa3b, v45
	v_exp_f32_e32 v40, v40
	v_mov_b32_e32 v44, v41
	v_add_f32_e32 v40, 1.0, v40
	v_rcp_f32_e32 v151, v40
	s_nop 0
	v_pk_mul_f32 v[40:41], v[150:151], v[44:45]
	v_lshlrev_b32_e32 v45, 16, v85
	v_mul_f32_e32 v40, v40, v41
	v_mul_f32_e32 v41, 0xbfb8aa3b, v45
	v_exp_f32_e32 v41, v41
	v_mov_b32_e32 v44, v42
	v_cvt_pk_bf16_f32 v40, v46, v40
	v_add_f32_e32 v41, 1.0, v41
	v_rcp_f32_e32 v151, v41
	s_nop 0
	v_pk_mul_f32 v[44:45], v[150:151], v[44:45]
	s_nop 0
	v_mul_f32_e32 v41, v44, v45
	v_and_b32_e32 v45, 0xffff0000, v85
	v_mul_f32_e32 v42, 0xbfb8aa3b, v45
	v_exp_f32_e32 v42, v42
	v_mov_b32_e32 v44, v43
	v_add_f32_e32 v42, 1.0, v42
	v_rcp_f32_e32 v151, v42
	s_nop 0
	v_pk_mul_f32 v[42:43], v[150:151], v[44:45]
	s_nop 0
	v_mul_f32_e32 v42, v42, v43
	v_cvt_pk_bf16_f32 v41, v41, v42
	ds_write_b64 v187, v[40:41] offset:160
	s_waitcnt vmcnt(15)
	v_lshlrev_b32_e32 v41, 16, v82
	v_mul_f32_e32 v40, 0xbfb8aa3b, v41
	v_exp_f32_e32 v40, v40
	s_nop 0
	v_add_f32_e32 v40, 1.0, v40
	v_rcp_f32_e32 v151, v40
	v_mov_b32_e32 v40, v36
	v_pk_mul_f32 v[40:41], v[150:151], v[40:41]
	s_nop 0
	v_mul_f32_e32 v42, v40, v41
	v_and_b32_e32 v41, 0xffff0000, v82
	v_mul_f32_e32 v36, 0xbfb8aa3b, v41
	v_exp_f32_e32 v36, v36
	v_mov_b32_e32 v40, v37
	v_add_f32_e32 v36, 1.0, v36
	v_rcp_f32_e32 v151, v36
	s_nop 0
	v_pk_mul_f32 v[36:37], v[150:151], v[40:41]
	v_lshlrev_b32_e32 v41, 16, v83
	v_mul_f32_e32 v36, v36, v37
	v_mul_f32_e32 v37, 0xbfb8aa3b, v41
	v_exp_f32_e32 v37, v37
	v_mov_b32_e32 v40, v38
	v_cvt_pk_bf16_f32 v36, v42, v36
	v_add_f32_e32 v37, 1.0, v37
	v_rcp_f32_e32 v151, v37
	s_nop 0
	v_pk_mul_f32 v[40:41], v[150:151], v[40:41]
	s_nop 0
	v_mul_f32_e32 v37, v40, v41
	v_and_b32_e32 v41, 0xffff0000, v83
	v_mul_f32_e32 v38, 0xbfb8aa3b, v41
	v_exp_f32_e32 v38, v38
	v_mov_b32_e32 v40, v39
	v_add_f32_e32 v38, 1.0, v38
	v_rcp_f32_e32 v151, v38
	s_nop 0
	v_pk_mul_f32 v[38:39], v[150:151], v[40:41]
	s_nop 0
	v_mul_f32_e32 v38, v38, v39
	v_cvt_pk_bf16_f32 v37, v37, v38
	ds_write_b64 v187, v[36:37] offset:192
	s_waitcnt vmcnt(15)
	v_lshlrev_b32_e32 v37, 16, v80
	v_mul_f32_e32 v36, 0xbfb8aa3b, v37
	v_exp_f32_e32 v36, v36
	s_nop 0
	v_add_f32_e32 v36, 1.0, v36
	v_rcp_f32_e32 v151, v36
	v_mov_b32_e32 v36, v32
	v_pk_mul_f32 v[36:37], v[150:151], v[36:37]
	s_nop 0
	v_mul_f32_e32 v38, v36, v37
	v_and_b32_e32 v37, 0xffff0000, v80
	v_mul_f32_e32 v32, 0xbfb8aa3b, v37
	v_exp_f32_e32 v32, v32
	v_mov_b32_e32 v36, v33
	v_add_f32_e32 v32, 1.0, v32
	v_rcp_f32_e32 v151, v32
	s_nop 0
	v_pk_mul_f32 v[32:33], v[150:151], v[36:37]
	v_lshlrev_b32_e32 v37, 16, v81
	v_mul_f32_e32 v32, v32, v33
	v_mul_f32_e32 v33, 0xbfb8aa3b, v37
	v_exp_f32_e32 v33, v33
	v_mov_b32_e32 v36, v34
	v_cvt_pk_bf16_f32 v32, v38, v32
	v_add_f32_e32 v33, 1.0, v33
	v_rcp_f32_e32 v151, v33
	s_nop 0
	v_pk_mul_f32 v[36:37], v[150:151], v[36:37]
	s_nop 0
	v_mul_f32_e32 v33, v36, v37
	v_and_b32_e32 v37, 0xffff0000, v81
	v_mul_f32_e32 v34, 0xbfb8aa3b, v37
	v_exp_f32_e32 v34, v34
	v_mov_b32_e32 v36, v35
	v_add_f32_e32 v34, 1.0, v34
	v_rcp_f32_e32 v151, v34
	s_nop 0
	v_pk_mul_f32 v[34:35], v[150:151], v[36:37]
	s_nop 0
	v_mul_f32_e32 v34, v34, v35
	v_cvt_pk_bf16_f32 v33, v33, v34
	ds_write_b64 v187, v[32:33] offset:224
	s_waitcnt vmcnt(15)
	v_lshlrev_b32_e32 v33, 16, v78
	v_mul_f32_e32 v32, 0xbfb8aa3b, v33
	v_exp_f32_e32 v32, v32
	s_nop 0
	v_add_f32_e32 v32, 1.0, v32
	v_rcp_f32_e32 v151, v32
	v_mov_b32_e32 v32, v28
	v_pk_mul_f32 v[32:33], v[150:151], v[32:33]
	s_nop 0
	v_mul_f32_e32 v34, v32, v33
	v_and_b32_e32 v33, 0xffff0000, v78
	v_mul_f32_e32 v28, 0xbfb8aa3b, v33
	v_exp_f32_e32 v28, v28
	v_mov_b32_e32 v32, v29
	v_add_f32_e32 v28, 1.0, v28
	v_rcp_f32_e32 v151, v28
	s_nop 0
	v_pk_mul_f32 v[28:29], v[150:151], v[32:33]
	v_lshlrev_b32_e32 v33, 16, v79
	v_mul_f32_e32 v28, v28, v29
	v_mul_f32_e32 v29, 0xbfb8aa3b, v33
	v_exp_f32_e32 v29, v29
	v_mov_b32_e32 v32, v30
	v_cvt_pk_bf16_f32 v28, v34, v28
	v_add_f32_e32 v29, 1.0, v29
	v_rcp_f32_e32 v151, v29
	s_nop 0
	v_pk_mul_f32 v[32:33], v[150:151], v[32:33]
	s_nop 0
	v_mul_f32_e32 v29, v32, v33
	v_and_b32_e32 v33, 0xffff0000, v79
	v_mul_f32_e32 v30, 0xbfb8aa3b, v33
	v_exp_f32_e32 v30, v30
	v_mov_b32_e32 v32, v31
	v_add_f32_e32 v30, 1.0, v30
	v_rcp_f32_e32 v151, v30
	s_nop 0
	v_pk_mul_f32 v[30:31], v[150:151], v[32:33]
	s_nop 0
	v_mul_f32_e32 v30, v30, v31
	v_cvt_pk_bf16_f32 v29, v29, v30
	ds_write_b64 v187, v[28:29] offset:256
	s_waitcnt vmcnt(15)
	v_lshlrev_b32_e32 v29, 16, v76
	v_mul_f32_e32 v28, 0xbfb8aa3b, v29
	v_exp_f32_e32 v28, v28
	s_nop 0
	v_add_f32_e32 v28, 1.0, v28
	v_rcp_f32_e32 v151, v28
	v_mov_b32_e32 v28, v24
	v_pk_mul_f32 v[28:29], v[150:151], v[28:29]
	s_nop 0
	v_mul_f32_e32 v30, v28, v29
	v_and_b32_e32 v29, 0xffff0000, v76
	v_mul_f32_e32 v24, 0xbfb8aa3b, v29
	v_exp_f32_e32 v24, v24
	v_mov_b32_e32 v28, v25
	v_add_f32_e32 v24, 1.0, v24
	v_rcp_f32_e32 v151, v24
	s_nop 0
	v_pk_mul_f32 v[24:25], v[150:151], v[28:29]
	v_lshlrev_b32_e32 v29, 16, v77
	v_mul_f32_e32 v24, v24, v25
	v_mul_f32_e32 v25, 0xbfb8aa3b, v29
	v_exp_f32_e32 v25, v25
	v_mov_b32_e32 v28, v26
	v_cvt_pk_bf16_f32 v24, v30, v24
	v_add_f32_e32 v25, 1.0, v25
	v_rcp_f32_e32 v151, v25
	s_nop 0
	v_pk_mul_f32 v[28:29], v[150:151], v[28:29]
	s_nop 0
	v_mul_f32_e32 v25, v28, v29
	v_and_b32_e32 v29, 0xffff0000, v77
	v_mul_f32_e32 v26, 0xbfb8aa3b, v29
	v_exp_f32_e32 v26, v26
	v_mov_b32_e32 v28, v27
	v_add_f32_e32 v26, 1.0, v26
	v_rcp_f32_e32 v151, v26
	s_nop 0
	v_pk_mul_f32 v[26:27], v[150:151], v[28:29]
	s_nop 0
	v_mul_f32_e32 v26, v26, v27
	v_cvt_pk_bf16_f32 v25, v25, v26
	ds_write_b64 v187, v[24:25] offset:288
	s_waitcnt vmcnt(15)
	v_lshlrev_b32_e32 v25, 16, v74
	v_mul_f32_e32 v24, 0xbfb8aa3b, v25
	v_exp_f32_e32 v24, v24
	s_nop 0
	v_add_f32_e32 v24, 1.0, v24
	v_rcp_f32_e32 v151, v24
	v_mov_b32_e32 v24, v20
	v_pk_mul_f32 v[24:25], v[150:151], v[24:25]
	s_nop 0
	v_mul_f32_e32 v26, v24, v25
	v_and_b32_e32 v25, 0xffff0000, v74
	v_mul_f32_e32 v20, 0xbfb8aa3b, v25
	v_exp_f32_e32 v20, v20
	v_mov_b32_e32 v24, v21
	v_add_f32_e32 v20, 1.0, v20
	v_rcp_f32_e32 v151, v20
	s_nop 0
	v_pk_mul_f32 v[20:21], v[150:151], v[24:25]
	v_lshlrev_b32_e32 v25, 16, v75
	v_mul_f32_e32 v20, v20, v21
	v_mul_f32_e32 v21, 0xbfb8aa3b, v25
	v_exp_f32_e32 v21, v21
	v_mov_b32_e32 v24, v22
	v_cvt_pk_bf16_f32 v20, v26, v20
	v_add_f32_e32 v21, 1.0, v21
	v_rcp_f32_e32 v151, v21
	s_nop 0
	v_pk_mul_f32 v[24:25], v[150:151], v[24:25]
	s_nop 0
	v_mul_f32_e32 v21, v24, v25
	v_and_b32_e32 v25, 0xffff0000, v75
	v_mul_f32_e32 v22, 0xbfb8aa3b, v25
	v_exp_f32_e32 v22, v22
	v_mov_b32_e32 v24, v23
	v_add_f32_e32 v22, 1.0, v22
	v_rcp_f32_e32 v151, v22
	s_nop 0
	v_pk_mul_f32 v[22:23], v[150:151], v[24:25]
	s_nop 0
	v_mul_f32_e32 v22, v22, v23
	v_cvt_pk_bf16_f32 v21, v21, v22
	ds_write_b64 v187, v[20:21] offset:320
	s_waitcnt vmcnt(15)
	v_lshlrev_b32_e32 v21, 16, v72
	v_mul_f32_e32 v20, 0xbfb8aa3b, v21
	v_exp_f32_e32 v20, v20
	s_nop 0
	v_add_f32_e32 v20, 1.0, v20
	v_rcp_f32_e32 v151, v20
	v_mov_b32_e32 v20, v16
	v_pk_mul_f32 v[20:21], v[150:151], v[20:21]
	s_nop 0
	v_mul_f32_e32 v22, v20, v21
	v_and_b32_e32 v21, 0xffff0000, v72
	v_mul_f32_e32 v16, 0xbfb8aa3b, v21
	v_exp_f32_e32 v16, v16
	v_mov_b32_e32 v20, v17
	v_add_f32_e32 v16, 1.0, v16
	v_rcp_f32_e32 v151, v16
	s_nop 0
	v_pk_mul_f32 v[16:17], v[150:151], v[20:21]
	v_lshlrev_b32_e32 v21, 16, v73
	v_mul_f32_e32 v16, v16, v17
	v_mul_f32_e32 v17, 0xbfb8aa3b, v21
	v_exp_f32_e32 v17, v17
	v_mov_b32_e32 v20, v18
	v_cvt_pk_bf16_f32 v16, v22, v16
	v_add_f32_e32 v17, 1.0, v17
	v_rcp_f32_e32 v151, v17
	s_nop 0
	v_pk_mul_f32 v[20:21], v[150:151], v[20:21]
	s_nop 0
	v_mul_f32_e32 v17, v20, v21
	v_and_b32_e32 v21, 0xffff0000, v73
	v_mul_f32_e32 v18, 0xbfb8aa3b, v21
	v_exp_f32_e32 v18, v18
	v_mov_b32_e32 v20, v19
	v_add_f32_e32 v18, 1.0, v18
	v_rcp_f32_e32 v151, v18
	s_nop 0
	v_pk_mul_f32 v[18:19], v[150:151], v[20:21]
	s_nop 0
	v_mul_f32_e32 v18, v18, v19
	v_cvt_pk_bf16_f32 v17, v17, v18
	ds_write_b64 v187, v[16:17] offset:352
	s_waitcnt vmcnt(15)
	v_lshlrev_b32_e32 v17, 16, v70
	v_mul_f32_e32 v16, 0xbfb8aa3b, v17
	v_exp_f32_e32 v16, v16
	s_nop 0
	v_add_f32_e32 v16, 1.0, v16
	v_rcp_f32_e32 v151, v16
	v_mov_b32_e32 v16, v12
	v_pk_mul_f32 v[16:17], v[150:151], v[16:17]
	s_nop 0
	v_mul_f32_e32 v18, v16, v17
	v_and_b32_e32 v17, 0xffff0000, v70
	v_mul_f32_e32 v12, 0xbfb8aa3b, v17
	v_exp_f32_e32 v12, v12
	v_mov_b32_e32 v16, v13
	v_add_f32_e32 v12, 1.0, v12
	v_rcp_f32_e32 v151, v12
	s_nop 0
	v_pk_mul_f32 v[12:13], v[150:151], v[16:17]
	v_lshlrev_b32_e32 v17, 16, v71
	v_mul_f32_e32 v12, v12, v13
	v_mul_f32_e32 v13, 0xbfb8aa3b, v17
	v_exp_f32_e32 v13, v13
	v_mov_b32_e32 v16, v14
	v_cvt_pk_bf16_f32 v12, v18, v12
	v_add_f32_e32 v13, 1.0, v13
	v_rcp_f32_e32 v151, v13
	s_nop 0
	v_pk_mul_f32 v[16:17], v[150:151], v[16:17]
	s_nop 0
	v_mul_f32_e32 v13, v16, v17
	v_and_b32_e32 v17, 0xffff0000, v71
	v_mul_f32_e32 v14, 0xbfb8aa3b, v17
	v_exp_f32_e32 v14, v14
	v_mov_b32_e32 v16, v15
	v_add_f32_e32 v14, 1.0, v14
	v_rcp_f32_e32 v151, v14
	s_nop 0
	v_pk_mul_f32 v[14:15], v[150:151], v[16:17]
	s_nop 0
	v_mul_f32_e32 v14, v14, v15
	v_cvt_pk_bf16_f32 v13, v13, v14
	ds_write_b64 v187, v[12:13] offset:384
	s_waitcnt vmcnt(15)
	v_lshlrev_b32_e32 v13, 16, v68
	v_mul_f32_e32 v12, 0xbfb8aa3b, v13
	v_exp_f32_e32 v12, v12
	s_nop 0
	v_add_f32_e32 v12, 1.0, v12
	v_rcp_f32_e32 v151, v12
	v_mov_b32_e32 v12, v8
	v_pk_mul_f32 v[12:13], v[150:151], v[12:13]
	s_nop 0
	v_mul_f32_e32 v14, v12, v13
	v_and_b32_e32 v13, 0xffff0000, v68
	v_mul_f32_e32 v8, 0xbfb8aa3b, v13
	v_exp_f32_e32 v8, v8
	v_mov_b32_e32 v12, v9
	v_add_f32_e32 v8, 1.0, v8
	v_rcp_f32_e32 v151, v8
	s_nop 0
	v_pk_mul_f32 v[8:9], v[150:151], v[12:13]
	v_lshlrev_b32_e32 v13, 16, v69
	v_mul_f32_e32 v8, v8, v9
	v_mul_f32_e32 v9, 0xbfb8aa3b, v13
	v_exp_f32_e32 v9, v9
	v_mov_b32_e32 v12, v10
	v_cvt_pk_bf16_f32 v8, v14, v8
	v_add_f32_e32 v9, 1.0, v9
	v_rcp_f32_e32 v151, v9
	s_nop 0
	v_pk_mul_f32 v[12:13], v[150:151], v[12:13]
	s_nop 0
	v_mul_f32_e32 v9, v12, v13
	v_and_b32_e32 v13, 0xffff0000, v69
	v_mul_f32_e32 v10, 0xbfb8aa3b, v13
	v_exp_f32_e32 v10, v10
	v_mov_b32_e32 v12, v11
	v_add_f32_e32 v10, 1.0, v10
	v_rcp_f32_e32 v151, v10
	s_nop 0
	v_pk_mul_f32 v[10:11], v[150:151], v[12:13]
	s_nop 0
	v_mul_f32_e32 v10, v10, v11
	v_cvt_pk_bf16_f32 v9, v9, v10
	ds_write_b64 v187, v[8:9] offset:416
	s_waitcnt vmcnt(15)
	v_lshlrev_b32_e32 v9, 16, v66
	v_mul_f32_e32 v8, 0xbfb8aa3b, v9
	v_exp_f32_e32 v8, v8
	s_nop 0
	v_add_f32_e32 v8, 1.0, v8
	v_rcp_f32_e32 v151, v8
	v_mov_b32_e32 v8, v4
	v_pk_mul_f32 v[8:9], v[150:151], v[8:9]
	s_nop 0
	v_mul_f32_e32 v10, v8, v9
	v_and_b32_e32 v9, 0xffff0000, v66
	v_mul_f32_e32 v4, 0xbfb8aa3b, v9
	v_exp_f32_e32 v4, v4
	v_mov_b32_e32 v8, v5
	v_add_f32_e32 v4, 1.0, v4
	v_rcp_f32_e32 v151, v4
	s_nop 0
	v_pk_mul_f32 v[4:5], v[150:151], v[8:9]
	v_lshlrev_b32_e32 v9, 16, v67
	v_mul_f32_e32 v4, v4, v5
	v_mul_f32_e32 v5, 0xbfb8aa3b, v9
	v_exp_f32_e32 v5, v5
	v_mov_b32_e32 v8, v6
	v_cvt_pk_bf16_f32 v4, v10, v4
	v_add_f32_e32 v5, 1.0, v5
	v_rcp_f32_e32 v151, v5
	s_nop 0
	v_pk_mul_f32 v[8:9], v[150:151], v[8:9]
	s_nop 0
	v_mul_f32_e32 v5, v8, v9
	v_and_b32_e32 v9, 0xffff0000, v67
	v_mul_f32_e32 v6, 0xbfb8aa3b, v9
	v_exp_f32_e32 v6, v6
	v_mov_b32_e32 v8, v7
	v_add_f32_e32 v6, 1.0, v6
	v_rcp_f32_e32 v151, v6
	s_nop 0
	v_pk_mul_f32 v[6:7], v[150:151], v[8:9]
	s_nop 0
	v_mul_f32_e32 v6, v6, v7
	v_cvt_pk_bf16_f32 v5, v5, v6
	ds_write_b64 v187, v[4:5] offset:448
	s_waitcnt vmcnt(15)
	v_lshlrev_b32_e32 v5, 16, v64
	v_mul_f32_e32 v4, 0xbfb8aa3b, v5
	v_exp_f32_e32 v4, v4
	s_nop 0
	v_add_f32_e32 v4, 1.0, v4
	v_rcp_f32_e32 v151, v4
	v_mov_b32_e32 v4, v0
	v_pk_mul_f32 v[4:5], v[150:151], v[4:5]
	s_nop 0
	v_mul_f32_e32 v6, v4, v5
	v_and_b32_e32 v5, 0xffff0000, v64
	v_mul_f32_e32 v0, 0xbfb8aa3b, v5
	v_exp_f32_e32 v0, v0
	v_mov_b32_e32 v4, v1
	v_add_f32_e32 v0, 1.0, v0
	v_rcp_f32_e32 v151, v0
	s_nop 0
	v_pk_mul_f32 v[0:1], v[150:151], v[4:5]
	v_lshlrev_b32_e32 v5, 16, v65
	v_mul_f32_e32 v0, v0, v1
	v_mul_f32_e32 v1, 0xbfb8aa3b, v5
	v_exp_f32_e32 v1, v1
	v_mov_b32_e32 v4, v2
	v_cvt_pk_bf16_f32 v0, v6, v0
	v_add_f32_e32 v1, 1.0, v1
	v_rcp_f32_e32 v151, v1
	s_nop 0
	v_pk_mul_f32 v[4:5], v[150:151], v[4:5]
	s_nop 0
	v_mul_f32_e32 v1, v4, v5
	v_and_b32_e32 v5, 0xffff0000, v65
	v_mul_f32_e32 v2, 0xbfb8aa3b, v5
	v_exp_f32_e32 v2, v2
	v_mov_b32_e32 v4, v3
	v_add_f32_e32 v2, 1.0, v2
	v_rcp_f32_e32 v151, v2
	s_nop 0
	v_pk_mul_f32 v[2:3], v[150:151], v[4:5]
	s_nop 0
	v_mul_f32_e32 v2, v2, v3
	v_cvt_pk_bf16_f32 v1, v1, v2
	ds_write_b64 v187, v[0:1] offset:480
	s_waitcnt lgkmcnt(0)
	v_lshl_add_u64 v[192:193], v[60:61], 0, v[188:189]
	ds_read_b128 v[202:205], v201
	ds_read_b128 v[206:209], v201 offset:1088
	ds_read_b128 v[210:213], v201 offset:2176
	ds_read_b128 v[214:217], v201 offset:3264
	ds_read_b128 v[218:221], v201 offset:4352
	ds_read_b128 v[222:225], v201 offset:5440
	ds_read_b128 v[226:229], v201 offset:6528
	ds_read_b128 v[230:233], v201 offset:7616
	s_waitcnt lgkmcnt(7)
	global_store_dwordx4 v[192:193], v[202:205], off
	s_waitcnt lgkmcnt(6)
	v_lshl_add_u64 v[192:193], v[192:193], 0, s[0:1]
	global_store_dwordx4 v[192:193], v[206:209], off
	s_waitcnt lgkmcnt(5)
	v_lshl_add_u64 v[192:193], v[192:193], 0, s[0:1]
	global_store_dwordx4 v[192:193], v[210:213], off
	s_waitcnt lgkmcnt(4)
	v_lshl_add_u64 v[192:193], v[192:193], 0, s[0:1]
	global_store_dwordx4 v[192:193], v[214:217], off
	s_waitcnt lgkmcnt(3)
	v_lshl_add_u64 v[192:193], v[192:193], 0, s[0:1]
	global_store_dwordx4 v[192:193], v[218:221], off
	s_waitcnt lgkmcnt(2)
	v_lshl_add_u64 v[192:193], v[192:193], 0, s[0:1]
	global_store_dwordx4 v[192:193], v[222:225], off
	s_waitcnt lgkmcnt(1)
	v_lshl_add_u64 v[192:193], v[192:193], 0, s[0:1]
	global_store_dwordx4 v[192:193], v[226:229], off
	s_waitcnt lgkmcnt(0)
	v_lshl_add_u64 v[192:193], v[192:193], 0, s[0:1]
	global_store_dwordx4 v[192:193], v[230:233], off

.LBB0_580:
	s_and_b64 vcc, exec, s[0:1]
	s_barrier
	s_waitcnt vmcnt(15)
	ds_write_b128 v153, v[24:27]
	s_waitcnt vmcnt(14)
	ds_write_b128 v154, v[28:31]
	s_waitcnt vmcnt(13)
	ds_write_b128 v155, v[32:35]
	s_waitcnt vmcnt(12)
	ds_write_b128 v156, v[36:39]
	s_waitcnt vmcnt(11)
	ds_write_b128 v157, v[44:47]
	s_waitcnt vmcnt(10)
	ds_write_b128 v158, v[48:51]
	s_waitcnt vmcnt(9)
	ds_write_b128 v159, v[52:55]
	s_waitcnt vmcnt(8)
	ds_write_b128 v160, v[56:59]
	s_waitcnt vmcnt(7)
	ds_write_b128 v161, v[64:67]
	s_waitcnt vmcnt(6)
	ds_write_b128 v162, v[68:71]
	s_waitcnt vmcnt(5)
	ds_write_b128 v164, v[76:79]
	s_waitcnt vmcnt(4)
	ds_write_b128 v166, v[80:83]
	s_waitcnt vmcnt(3)
	ds_write_b128 v167, v[84:87]
	s_waitcnt vmcnt(2)
	ds_write_b128 v174, v[88:91]
	s_waitcnt vmcnt(1)
	ds_write_b128 v175, v[96:99]
	s_waitcnt vmcnt(0)
	ds_write_b128 v177, v[100:103]
	s_waitcnt lgkmcnt(0)
	s_barrier
	s_cbranch_vccnz .LBB0_582
	v_readlane_b32 s0, v235, 14
	v_readlane_b32 s1, v235, 15
	v_and_b32_e32 v182, 63, v194
	v_lshrrev_b32_e32 v183, 5, v182
	v_and_b32_e32 v184, 31, v182
	v_and_b32_e32 v185, 15, v182
	v_lshrrev_b32_e32 v186, 4, v182
	v_sub_u32_e32 v188, v183, v185
	v_mul_i32_i24_e32 v188, 0x3000, v188
	v_lshl_add_u32 v188, v184, 4, v188
	v_lshlrev_b32_e32 v189, 3, v186
	v_sub_u32_e32 v188, v188, v189
	v_ashrrev_i32_e32 v189, 31, v188
	v_lshrrev_b32_e32 v187, 6, v194
	v_mul_u32_u24_e32 v187, 0x4400, v187
	v_mul_u32_u24_e32 v201, 0x220, v183
	v_add_u32_e32 v201, v201, v187
	v_lshl_add_u32 v201, v184, 4, v201
	v_mul_u32_u24_e32 v182, 0x220, v185
	v_add_u32_e32 v187, v187, v182
	v_lshl_add_u32 v187, v186, 3, v187
	v_lshlrev_b32_e32 v192, 3, v163
	v_mov_b32_e32 v193, 0
	v_mov_b64_e32 v[190:191], s[0:1]
	v_mad_i64_i32 v[190:191], vcc, v165, s66, v[190:191]
	v_lshl_add_u64 v[190:191], v[190:191], 0, v[192:193]
	v_lshl_add_u64 v[190:191], v[190:191], 0, v[188:189]
	s_mov_b64 s[0:1], 0x6000
	s_movk_i32 vcc_lo, 0x2000
	s_mov_b32 vcc_hi, 0
	v_lshl_add_u64 v[190:191], v[190:191], 0, vcc
	global_load_dwordx4 v[202:205], v[190:191], off offset:2048
	v_lshl_add_u64 v[190:191], v[190:191], 0, s[0:1]
	global_load_dwordx4 v[206:209], v[190:191], off offset:2048
	v_lshl_add_u64 v[190:191], v[190:191], 0, s[0:1]
	global_load_dwordx4 v[210:213], v[190:191], off offset:2048
	v_lshl_add_u64 v[190:191], v[190:191], 0, s[0:1]
	global_load_dwordx4 v[214:217], v[190:191], off offset:2048
	v_lshl_add_u64 v[190:191], v[190:191], 0, s[0:1]
	global_load_dwordx4 v[218:221], v[190:191], off offset:2048
	v_lshl_add_u64 v[190:191], v[190:191], 0, s[0:1]
	global_load_dwordx4 v[222:225], v[190:191], off offset:2048
	v_lshl_add_u64 v[190:191], v[190:191], 0, s[0:1]
	global_load_dwordx4 v[226:229], v[190:191], off offset:2048
	v_lshl_add_u64 v[190:191], v[190:191], 0, s[0:1]
	global_load_dwordx4 v[230:233], v[190:191], off offset:2048
	ds_read_b128 v[0:3], v176
	ds_read_b128 v[4:7], v176 offset:8704
	ds_read_b128 v[8:11], v176 offset:17408
	ds_read_b128 v[12:15], v176 offset:26112
	ds_read_b128 v[16:19], v176 offset:34816
	ds_read_b128 v[20:23], v176 offset:43520
	ds_read_b128 v[24:27], v176 offset:52224
	ds_read_b128 v[28:31], v176 offset:60928
	v_add_u32_e32 v32, 0x11000, v172
	v_add_u32_e32 v36, 0x13200, v172
	v_add_u32_e32 v40, 0x15400, v172
	v_add_u32_e32 v44, 0x17600, v172
	v_add_u32_e32 v48, 0x19800, v172
	v_add_u32_e32 v52, 0x1ba00, v172
	v_add_u32_e32 v56, 0x1dc00, v172
	v_add_u32_e32 v60, 0x1fe00, v172
	ds_read_b128 v[32:35], v32
	ds_read_b128 v[36:39], v36
	ds_read_b128 v[40:43], v40
	ds_read_b128 v[44:47], v44
	ds_read_b128 v[48:51], v48
	ds_read_b128 v[52:55], v52
	ds_read_b128 v[56:59], v56
	ds_read_b128 v[60:63], v60
	s_waitcnt lgkmcnt(14)
	v_mfma_f32_16x16x32_bf16 v[0:3], v[0:3], v[120:123], 0
	v_mfma_f32_16x16x32_bf16 v[4:7], v[4:7], v[120:123], 0
	s_waitcnt lgkmcnt(13)
	v_mfma_f32_16x16x32_bf16 v[8:11], v[8:11], v[120:123], 0
	s_waitcnt lgkmcnt(12)
	v_mfma_f32_16x16x32_bf16 v[12:15], v[12:15], v[120:123], 0
	s_waitcnt lgkmcnt(11)
	v_mfma_f32_16x16x32_bf16 v[16:19], v[16:19], v[120:123], 0
	s_waitcnt lgkmcnt(10)
	v_mfma_f32_16x16x32_bf16 v[20:23], v[20:23], v[120:123], 0
	s_waitcnt lgkmcnt(9)
	v_mfma_f32_16x16x32_bf16 v[24:27], v[24:27], v[120:123], 0
	s_waitcnt lgkmcnt(8)
	v_mfma_f32_16x16x32_bf16 v[28:31], v[28:31], v[120:123], 0
	ds_read_b128 v[64:67], v176 offset:60992
	ds_read_b128 v[68:71], v176 offset:52288
	ds_read_b128 v[72:75], v176 offset:43584
	ds_read_b128 v[76:79], v176 offset:34880
	ds_read_b128 v[80:83], v176 offset:26176
	ds_read_b128 v[84:87], v176 offset:17472
	ds_read_b128 v[88:91], v176 offset:8768
	ds_read_b128 v[92:95], v176 offset:64
	s_waitcnt lgkmcnt(14)
	v_mfma_f32_16x16x32_bf16 v[32:35], v[32:35], v[120:123], 0
	v_mfma_f32_16x16x32_bf16 v[36:39], v[36:39], v[120:123], 0
	s_waitcnt lgkmcnt(13)
	v_mfma_f32_16x16x32_bf16 v[40:43], v[40:43], v[120:123], 0
	s_waitcnt lgkmcnt(12)
	v_mfma_f32_16x16x32_bf16 v[44:47], v[44:47], v[120:123], 0
	s_waitcnt lgkmcnt(11)
	v_mfma_f32_16x16x32_bf16 v[48:51], v[48:51], v[120:123], 0
	s_waitcnt lgkmcnt(10)
	v_mfma_f32_16x16x32_bf16 v[52:55], v[52:55], v[120:123], 0
	s_waitcnt lgkmcnt(9)
	v_mfma_f32_16x16x32_bf16 v[56:59], v[56:59], v[120:123], 0
	s_waitcnt lgkmcnt(8)
	v_mfma_f32_16x16x32_bf16 v[60:63], v[60:63], v[120:123], 0
	v_add_u32_e32 v96, 0x11040, v172
	v_add_u32_e32 v100, 0x13240, v172
	v_add_u32_e32 v104, 0x15440, v172
	v_add_u32_e32 v120, 0x17640, v172
	v_add_u32_e32 v136, 0x19840, v172
	v_add_u32_e32 v140, 0x1ba40, v172
	v_add_u32_e32 v144, 0x1dc40, v172
	ds_read_b128 v[96:99], v96
	ds_read_b128 v[100:103], v100
	ds_read_b128 v[104:107], v104
	ds_read_b128 v[120:123], v120
	ds_read_b128 v[136:139], v136
	ds_read_b128 v[140:143], v140
	v_add_u32_e32 v145, 0x1fe40, v172
	ds_read_b128 v[154:157], v144
	ds_read_b128 v[158:161], v145
	s_waitcnt lgkmcnt(8)
	v_mfma_f32_16x16x32_bf16 v[0:3], v[92:95], v[108:111], v[0:3]
	v_mfma_f32_16x16x32_bf16 v[4:7], v[88:91], v[108:111], v[4:7]
	v_mfma_f32_16x16x32_bf16 v[8:11], v[84:87], v[108:111], v[8:11]
	v_mfma_f32_16x16x32_bf16 v[12:15], v[80:83], v[108:111], v[12:15]
	v_mfma_f32_16x16x32_bf16 v[16:19], v[76:79], v[108:111], v[16:19]
	v_mfma_f32_16x16x32_bf16 v[20:23], v[72:75], v[108:111], v[20:23]
	v_mfma_f32_16x16x32_bf16 v[24:27], v[68:71], v[108:111], v[24:27]
	v_mfma_f32_16x16x32_bf16 v[28:31], v[64:67], v[108:111], v[28:31]
	ds_read_b128 v[64:67], v176 offset:61056
	ds_read_b128 v[68:71], v176 offset:52352
	ds_read_b128 v[72:75], v176 offset:43648
	ds_read_b128 v[76:79], v176 offset:34944
	ds_read_b128 v[80:83], v176 offset:26240
	ds_read_b128 v[84:87], v176 offset:17536
	ds_read_b128 v[88:91], v176 offset:8832
	ds_read_b128 v[92:95], v176 offset:128
	s_waitcnt lgkmcnt(14)
	v_mfma_f32_16x16x32_bf16 v[32:35], v[96:99], v[108:111], v[32:35]
	v_mfma_f32_16x16x32_bf16 v[36:39], v[100:103], v[108:111], v[36:39]
	s_waitcnt lgkmcnt(13)
	v_mfma_f32_16x16x32_bf16 v[40:43], v[104:107], v[108:111], v[40:43]
	s_waitcnt lgkmcnt(12)
	v_mfma_f32_16x16x32_bf16 v[44:47], v[120:123], v[108:111], v[44:47]
	s_waitcnt lgkmcnt(11)
	v_mfma_f32_16x16x32_bf16 v[48:51], v[136:139], v[108:111], v[48:51]
	s_waitcnt lgkmcnt(10)
	v_mfma_f32_16x16x32_bf16 v[52:55], v[140:143], v[108:111], v[52:55]
	s_waitcnt lgkmcnt(9)
	v_mfma_f32_16x16x32_bf16 v[56:59], v[154:157], v[108:111], v[56:59]
	s_waitcnt lgkmcnt(8)
	v_mfma_f32_16x16x32_bf16 v[60:63], v[158:161], v[108:111], v[60:63]
	v_add_u32_e32 v96, 0x11080, v172
	v_add_u32_e32 v100, 0x13280, v172
	v_add_u32_e32 v104, 0x15480, v172
	v_add_u32_e32 v108, 0x17680, v172
	v_add_u32_e32 v120, 0x19880, v172
	v_add_u32_e32 v136, 0x1ba80, v172
	v_add_u32_e32 v140, 0x1dc80, v172
	ds_read_b128 v[96:99], v96
	ds_read_b128 v[100:103], v100
	ds_read_b128 v[104:107], v104
	ds_read_b128 v[108:111], v108
	ds_read_b128 v[120:123], v120
	ds_read_b128 v[136:139], v136
	v_add_u32_e32 v144, 0x1fe80, v172
	ds_read_b128 v[140:143], v140
	ds_read_b128 v[154:157], v144
	s_waitcnt lgkmcnt(8)
	v_mfma_f32_16x16x32_bf16 v[0:3], v[92:95], v[116:119], v[0:3]
	v_mfma_f32_16x16x32_bf16 v[4:7], v[88:91], v[116:119], v[4:7]
	v_mfma_f32_16x16x32_bf16 v[8:11], v[84:87], v[116:119], v[8:11]
	v_mfma_f32_16x16x32_bf16 v[12:15], v[80:83], v[116:119], v[12:15]
	v_mfma_f32_16x16x32_bf16 v[16:19], v[76:79], v[116:119], v[16:19]
	v_mfma_f32_16x16x32_bf16 v[20:23], v[72:75], v[116:119], v[20:23]
	v_mfma_f32_16x16x32_bf16 v[24:27], v[68:71], v[116:119], v[24:27]
	v_mfma_f32_16x16x32_bf16 v[28:31], v[64:67], v[116:119], v[28:31]
	ds_read_b128 v[64:67], v176 offset:61120
	ds_read_b128 v[68:71], v176 offset:52416
	ds_read_b128 v[72:75], v176 offset:43712
	ds_read_b128 v[76:79], v176 offset:35008
	ds_read_b128 v[80:83], v176 offset:26304
	ds_read_b128 v[84:87], v176 offset:17600
	ds_read_b128 v[88:91], v176 offset:8896
	ds_read_b128 v[92:95], v176 offset:192
	s_waitcnt lgkmcnt(14)
	v_mfma_f32_16x16x32_bf16 v[32:35], v[96:99], v[116:119], v[32:35]
	v_mfma_f32_16x16x32_bf16 v[36:39], v[100:103], v[116:119], v[36:39]
	s_waitcnt lgkmcnt(13)
	v_mfma_f32_16x16x32_bf16 v[40:43], v[104:107], v[116:119], v[40:43]
	s_waitcnt lgkmcnt(12)
	v_mfma_f32_16x16x32_bf16 v[44:47], v[108:111], v[116:119], v[44:47]
	s_waitcnt lgkmcnt(11)
	v_mfma_f32_16x16x32_bf16 v[48:51], v[120:123], v[116:119], v[48:51]
	s_waitcnt lgkmcnt(10)
	v_mfma_f32_16x16x32_bf16 v[52:55], v[136:139], v[116:119], v[52:55]
	s_waitcnt lgkmcnt(9)
	v_mfma_f32_16x16x32_bf16 v[56:59], v[140:143], v[116:119], v[56:59]
	s_waitcnt lgkmcnt(8)
	v_mfma_f32_16x16x32_bf16 v[60:63], v[154:157], v[116:119], v[60:63]
	v_add_u32_e32 v96, 0x110c0, v172
	v_add_u32_e32 v100, 0x132c0, v172
	v_add_u32_e32 v104, 0x154c0, v172
	v_add_u32_e32 v108, 0x176c0, v172
	v_add_u32_e32 v116, 0x198c0, v172
	v_add_u32_e32 v120, 0x1bac0, v172
	v_add_u32_e32 v136, 0x1dcc0, v172
	v_add_u32_e32 v140, 0x1fec0, v172
	ds_read_b128 v[96:99], v96
	ds_read_b128 v[100:103], v100
	ds_read_b128 v[104:107], v104
	ds_read_b128 v[108:111], v108
	ds_read_b128 v[116:119], v116
	ds_read_b128 v[120:123], v120
	ds_read_b128 v[136:139], v136
	ds_read_b128 v[140:143], v140
	s_waitcnt lgkmcnt(8)
	v_mfma_f32_16x16x32_bf16 v[0:3], v[92:95], v[124:127], v[0:3]
	v_mfma_f32_16x16x32_bf16 v[4:7], v[88:91], v[124:127], v[4:7]
	v_mfma_f32_16x16x32_bf16 v[8:11], v[84:87], v[124:127], v[8:11]
	v_mfma_f32_16x16x32_bf16 v[12:15], v[80:83], v[124:127], v[12:15]
	v_mfma_f32_16x16x32_bf16 v[16:19], v[76:79], v[124:127], v[16:19]
	v_mfma_f32_16x16x32_bf16 v[20:23], v[72:75], v[124:127], v[20:23]
	v_mfma_f32_16x16x32_bf16 v[24:27], v[68:71], v[124:127], v[24:27]
	v_mfma_f32_16x16x32_bf16 v[28:31], v[64:67], v[124:127], v[28:31]
	ds_read_b128 v[64:67], v176 offset:61184
	ds_read_b128 v[68:71], v176 offset:52480
	ds_read_b128 v[72:75], v176 offset:43776
	ds_read_b128 v[76:79], v176 offset:35072
	ds_read_b128 v[80:83], v176 offset:26368
	ds_read_b128 v[84:87], v176 offset:17664
	ds_read_b128 v[88:91], v176 offset:8960
	ds_read_b128 v[92:95], v176 offset:256
	s_waitcnt lgkmcnt(14)
	v_mfma_f32_16x16x32_bf16 v[32:35], v[96:99], v[124:127], v[32:35]
	v_mfma_f32_16x16x32_bf16 v[36:39], v[100:103], v[124:127], v[36:39]
	s_waitcnt lgkmcnt(13)
	v_mfma_f32_16x16x32_bf16 v[40:43], v[104:107], v[124:127], v[40:43]
	s_waitcnt lgkmcnt(12)
	v_mfma_f32_16x16x32_bf16 v[44:47], v[108:111], v[124:127], v[44:47]
	s_waitcnt lgkmcnt(11)
	v_mfma_f32_16x16x32_bf16 v[48:51], v[116:119], v[124:127], v[48:51]
	s_waitcnt lgkmcnt(10)
	v_mfma_f32_16x16x32_bf16 v[52:55], v[120:123], v[124:127], v[52:55]
	s_waitcnt lgkmcnt(9)
	v_mfma_f32_16x16x32_bf16 v[56:59], v[136:139], v[124:127], v[56:59]
	s_waitcnt lgkmcnt(8)
	v_mfma_f32_16x16x32_bf16 v[60:63], v[140:143], v[124:127], v[60:63]
	v_add_u32_e32 v96, 0x11100, v172
	v_add_u32_e32 v100, 0x13300, v172
	v_add_u32_e32 v104, 0x15500, v172
	v_add_u32_e32 v108, 0x17700, v172
	v_add_u32_e32 v116, 0x19900, v172
	v_add_u32_e32 v120, 0x1bb00, v172
	v_add_u32_e32 v124, 0x1dd00, v172
	v_add_u32_e32 v136, 0x1ff00, v172
	ds_read_b128 v[96:99], v96
	ds_read_b128 v[100:103], v100
	ds_read_b128 v[104:107], v104
	ds_read_b128 v[108:111], v108
	ds_read_b128 v[116:119], v116
	ds_read_b128 v[120:123], v120
	ds_read_b128 v[124:127], v124
	ds_read_b128 v[136:139], v136
	s_waitcnt lgkmcnt(8)
	v_mfma_f32_16x16x32_bf16 v[0:3], v[92:95], v[112:115], v[0:3]
	v_mfma_f32_16x16x32_bf16 v[4:7], v[88:91], v[112:115], v[4:7]
	v_mfma_f32_16x16x32_bf16 v[8:11], v[84:87], v[112:115], v[8:11]
	v_mfma_f32_16x16x32_bf16 v[12:15], v[80:83], v[112:115], v[12:15]
	v_mfma_f32_16x16x32_bf16 v[16:19], v[76:79], v[112:115], v[16:19]
	v_mfma_f32_16x16x32_bf16 v[20:23], v[72:75], v[112:115], v[20:23]
	v_mfma_f32_16x16x32_bf16 v[24:27], v[68:71], v[112:115], v[24:27]
	v_mfma_f32_16x16x32_bf16 v[28:31], v[64:67], v[112:115], v[28:31]
	ds_read_b128 v[64:67], v176 offset:61248
	ds_read_b128 v[68:71], v176 offset:52544
	ds_read_b128 v[72:75], v176 offset:43840
	ds_read_b128 v[76:79], v176 offset:35136
	ds_read_b128 v[80:83], v176 offset:26432
	ds_read_b128 v[84:87], v176 offset:17728
	ds_read_b128 v[88:91], v176 offset:9024
	ds_read_b128 v[92:95], v176 offset:320
	s_waitcnt lgkmcnt(14)
	v_mfma_f32_16x16x32_bf16 v[32:35], v[96:99], v[112:115], v[32:35]
	v_mfma_f32_16x16x32_bf16 v[36:39], v[100:103], v[112:115], v[36:39]
	s_waitcnt lgkmcnt(13)
	v_mfma_f32_16x16x32_bf16 v[40:43], v[104:107], v[112:115], v[40:43]
	s_waitcnt lgkmcnt(12)
	v_mfma_f32_16x16x32_bf16 v[44:47], v[108:111], v[112:115], v[44:47]
	s_waitcnt lgkmcnt(11)
	v_mfma_f32_16x16x32_bf16 v[48:51], v[116:119], v[112:115], v[48:51]
	s_waitcnt lgkmcnt(10)
	v_mfma_f32_16x16x32_bf16 v[52:55], v[120:123], v[112:115], v[52:55]
	s_waitcnt lgkmcnt(9)
	v_mfma_f32_16x16x32_bf16 v[56:59], v[124:127], v[112:115], v[56:59]
	s_waitcnt lgkmcnt(8)
	v_mfma_f32_16x16x32_bf16 v[60:63], v[136:139], v[112:115], v[60:63]
	v_add_u32_e32 v96, 0x11140, v172
	v_add_u32_e32 v100, 0x13340, v172
	v_add_u32_e32 v104, 0x15540, v172
	v_add_u32_e32 v108, 0x17740, v172
	v_add_u32_e32 v112, 0x19940, v172
	v_add_u32_e32 v116, 0x1bb40, v172
	v_add_u32_e32 v120, 0x1dd40, v172
	v_add_u32_e32 v124, 0x1ff40, v172
	ds_read_b128 v[96:99], v96
	ds_read_b128 v[100:103], v100
	ds_read_b128 v[104:107], v104
	ds_read_b128 v[108:111], v108
	ds_read_b128 v[112:115], v112
	ds_read_b128 v[116:119], v116
	ds_read_b128 v[120:123], v120
	ds_read_b128 v[124:127], v124
	s_waitcnt lgkmcnt(8)
	v_mfma_f32_16x16x32_bf16 v[0:3], v[92:95], v[132:135], v[0:3]
	v_mfma_f32_16x16x32_bf16 v[4:7], v[88:91], v[132:135], v[4:7]
	v_mfma_f32_16x16x32_bf16 v[8:11], v[84:87], v[132:135], v[8:11]
	v_mfma_f32_16x16x32_bf16 v[12:15], v[80:83], v[132:135], v[12:15]
	v_mfma_f32_16x16x32_bf16 v[16:19], v[76:79], v[132:135], v[16:19]
	v_mfma_f32_16x16x32_bf16 v[20:23], v[72:75], v[132:135], v[20:23]
	v_mfma_f32_16x16x32_bf16 v[24:27], v[68:71], v[132:135], v[24:27]
	v_mfma_f32_16x16x32_bf16 v[28:31], v[64:67], v[132:135], v[28:31]
	ds_read_b128 v[64:67], v176 offset:61312
	ds_read_b128 v[68:71], v176 offset:52608
	ds_read_b128 v[72:75], v176 offset:43904
	ds_read_b128 v[76:79], v176 offset:35200
	ds_read_b128 v[80:83], v176 offset:26496
	ds_read_b128 v[84:87], v176 offset:17792
	ds_read_b128 v[88:91], v176 offset:9088
	ds_read_b128 v[92:95], v176 offset:384
	s_waitcnt lgkmcnt(14)
	v_mfma_f32_16x16x32_bf16 v[32:35], v[96:99], v[132:135], v[32:35]
	v_mfma_f32_16x16x32_bf16 v[36:39], v[100:103], v[132:135], v[36:39]
	s_waitcnt lgkmcnt(13)
	v_mfma_f32_16x16x32_bf16 v[40:43], v[104:107], v[132:135], v[40:43]
	s_waitcnt lgkmcnt(12)
	v_mfma_f32_16x16x32_bf16 v[44:47], v[108:111], v[132:135], v[44:47]
	s_waitcnt lgkmcnt(11)
	v_mfma_f32_16x16x32_bf16 v[48:51], v[112:115], v[132:135], v[48:51]
	s_waitcnt lgkmcnt(10)
	v_mfma_f32_16x16x32_bf16 v[52:55], v[116:119], v[132:135], v[52:55]
	s_waitcnt lgkmcnt(9)
	v_mfma_f32_16x16x32_bf16 v[56:59], v[120:123], v[132:135], v[56:59]
	s_waitcnt lgkmcnt(8)
	v_mfma_f32_16x16x32_bf16 v[60:63], v[124:127], v[132:135], v[60:63]
	v_add_u32_e32 v96, 0x11180, v172
	v_add_u32_e32 v100, 0x13380, v172
	v_add_u32_e32 v104, 0x15580, v172
	v_add_u32_e32 v108, 0x17780, v172
	v_add_u32_e32 v112, 0x19980, v172
	v_add_u32_e32 v116, 0x1bb80, v172
	v_add_u32_e32 v120, 0x1dd80, v172
	v_add_u32_e32 v124, 0x1ff80, v172
	ds_read_b128 v[96:99], v96
	ds_read_b128 v[100:103], v100
	ds_read_b128 v[104:107], v104
	ds_read_b128 v[108:111], v108
	ds_read_b128 v[112:115], v112
	ds_read_b128 v[116:119], v116
	ds_read_b128 v[120:123], v120
	ds_read_b128 v[124:127], v124
	s_waitcnt lgkmcnt(8)
	v_mfma_f32_16x16x32_bf16 v[0:3], v[92:95], v[146:149], v[0:3]
	v_mfma_f32_16x16x32_bf16 v[4:7], v[88:91], v[146:149], v[4:7]
	v_mfma_f32_16x16x32_bf16 v[8:11], v[84:87], v[146:149], v[8:11]
	v_mfma_f32_16x16x32_bf16 v[12:15], v[80:83], v[146:149], v[12:15]
	v_mfma_f32_16x16x32_bf16 v[16:19], v[76:79], v[146:149], v[16:19]
	v_mfma_f32_16x16x32_bf16 v[20:23], v[72:75], v[146:149], v[20:23]
	v_mfma_f32_16x16x32_bf16 v[24:27], v[68:71], v[146:149], v[24:27]
	v_mfma_f32_16x16x32_bf16 v[28:31], v[64:67], v[146:149], v[28:31]
	ds_read_b128 v[64:67], v176 offset:61376
	ds_read_b128 v[68:71], v176 offset:52672
	ds_read_b128 v[72:75], v176 offset:43968
	ds_read_b128 v[76:79], v176 offset:35264
	ds_read_b128 v[80:83], v176 offset:26560
	ds_read_b128 v[84:87], v176 offset:17856
	ds_read_b128 v[88:91], v176 offset:9152
	ds_read_b128 v[92:95], v176 offset:448
	s_waitcnt lgkmcnt(14)
	v_mfma_f32_16x16x32_bf16 v[96:99], v[96:99], v[146:149], v[32:35]
	v_mfma_f32_16x16x32_bf16 v[100:103], v[100:103], v[146:149], v[36:39]
	s_waitcnt lgkmcnt(13)
	v_mfma_f32_16x16x32_bf16 v[104:107], v[104:107], v[146:149], v[40:43]
	s_waitcnt lgkmcnt(12)
	v_mfma_f32_16x16x32_bf16 v[108:111], v[108:111], v[146:149], v[44:47]
	s_waitcnt lgkmcnt(11)
	v_mfma_f32_16x16x32_bf16 v[112:115], v[112:115], v[146:149], v[48:51]
	s_waitcnt lgkmcnt(10)
	v_mfma_f32_16x16x32_bf16 v[116:119], v[116:119], v[146:149], v[52:55]
	s_waitcnt lgkmcnt(9)
	v_mfma_f32_16x16x32_bf16 v[120:123], v[120:123], v[146:149], v[56:59]
	s_waitcnt lgkmcnt(8)
	v_mfma_f32_16x16x32_bf16 v[124:127], v[124:127], v[146:149], v[60:63]
	v_add_u32_e32 v32, 0x111c0, v172
	v_add_u32_e32 v33, 0x133c0, v172
	ds_read_b128 v[132:135], v32
	ds_read_b128 v[136:139], v33
	v_add_u32_e32 v32, 0x155c0, v172
	v_add_u32_e32 v33, 0x177c0, v172
	ds_read_b128 v[140:143], v32
	ds_read_b128 v[144:147], v33
	v_add_u32_e32 v32, 0x199c0, v172
	v_add_u32_e32 v33, 0x1bbc0, v172
	ds_read_b128 v[148:151], v32
	ds_read_b128 v[154:157], v33
	v_add_u32_e32 v32, 0x1ddc0, v172
	v_add_u32_e32 v33, 0x1ffc0, v172
	ds_read_b128 v[158:161], v32
	ds_read_b128 v[174:177], v33
	s_waitcnt lgkmcnt(8)
	v_mfma_f32_16x16x32_bf16 v[60:63], v[92:95], v[128:131], v[0:3]
	v_mfma_f32_16x16x32_bf16 v[56:59], v[88:91], v[128:131], v[4:7]
	v_mfma_f32_16x16x32_bf16 v[52:55], v[84:87], v[128:131], v[8:11]
	v_mfma_f32_16x16x32_bf16 v[48:51], v[80:83], v[128:131], v[12:15]
	v_mfma_f32_16x16x32_bf16 v[44:47], v[76:79], v[128:131], v[16:19]
	v_mfma_f32_16x16x32_bf16 v[40:43], v[72:75], v[128:131], v[20:23]
	v_mfma_f32_16x16x32_bf16 v[36:39], v[68:71], v[128:131], v[24:27]
	v_mfma_f32_16x16x32_bf16 v[32:35], v[64:67], v[128:131], v[28:31]
	s_waitcnt lgkmcnt(7)
	v_mfma_f32_16x16x32_bf16 v[28:31], v[132:135], v[128:131], v[96:99]
	s_waitcnt lgkmcnt(6)
	v_mfma_f32_16x16x32_bf16 v[24:27], v[136:139], v[128:131], v[100:103]
	s_waitcnt lgkmcnt(5)
	v_mfma_f32_16x16x32_bf16 v[20:23], v[140:143], v[128:131], v[104:107]
	s_waitcnt lgkmcnt(4)
	v_mfma_f32_16x16x32_bf16 v[16:19], v[144:147], v[128:131], v[108:111]
	s_waitcnt lgkmcnt(3)
	v_mfma_f32_16x16x32_bf16 v[12:15], v[148:151], v[128:131], v[112:115]
	s_waitcnt lgkmcnt(2)
	v_mfma_f32_16x16x32_bf16 v[8:11], v[154:157], v[128:131], v[116:119]
	s_waitcnt lgkmcnt(1)
	v_mfma_f32_16x16x32_bf16 v[4:7], v[158:161], v[128:131], v[120:123]
	s_waitcnt lgkmcnt(0)
	v_mfma_f32_16x16x32_bf16 v[0:3], v[174:177], v[128:131], v[124:127]
	v_readlane_b32 s0, v235, 14
	v_readlane_b32 s1, v235, 15
	v_lshlrev_b32_e32 v172, 3, v163
	s_nop 0
	v_mov_b64_e32 v[64:65], s[0:1]
	v_mad_i64_i32 v[64:65], s[0:1], v165, s66, v[64:65]
	v_lshl_add_u64 v[94:95], v[64:65], 0, v[172:173]
	v_add_co_u32_e32 v64, vcc, s92, v94
	s_nop 1
	v_addc_co_u32_e32 v65, vcc, 0, v95, vcc
	s_barrier
	s_mov_b64 s[0:1], 0x6000
	s_waitcnt vmcnt(7)
	ds_write_b128 v201, v[202:205]
	s_waitcnt vmcnt(6)
	ds_write_b128 v201, v[206:209] offset:1088
	s_waitcnt vmcnt(5)
	ds_write_b128 v201, v[210:213] offset:2176
	s_waitcnt vmcnt(4)
	ds_write_b128 v201, v[214:217] offset:3264
	s_waitcnt vmcnt(3)
	ds_write_b128 v201, v[218:221] offset:4352
	s_waitcnt vmcnt(2)
	ds_write_b128 v201, v[222:225] offset:5440
	s_waitcnt vmcnt(1)
	ds_write_b128 v201, v[226:229] offset:6528
	s_waitcnt vmcnt(0)
	ds_write_b128 v201, v[230:233] offset:7616
	ds_read_b64 v[96:97], v187
	ds_read_b64 v[92:93], v187 offset:32
	ds_read_b64 v[90:91], v187 offset:64
	ds_read_b64 v[88:89], v187 offset:96
	ds_read_b64 v[86:87], v187 offset:128
	ds_read_b64 v[84:85], v187 offset:160
	ds_read_b64 v[82:83], v187 offset:192
	ds_read_b64 v[80:81], v187 offset:224
	ds_read_b64 v[78:79], v187 offset:256
	ds_read_b64 v[76:77], v187 offset:288
	ds_read_b64 v[74:75], v187 offset:320
	ds_read_b64 v[72:73], v187 offset:352
	ds_read_b64 v[70:71], v187 offset:384
	ds_read_b64 v[68:69], v187 offset:416
	ds_read_b64 v[66:67], v187 offset:448
	ds_read_b64 v[64:65], v187 offset:480
	s_waitcnt lgkmcnt(0)
	s_waitcnt vmcnt(15)
	v_lshlrev_b32_e32 v99, 16, v96
	v_mul_f32_e32 v98, 0xbfb8aa3b, v99
	v_exp_f32_e32 v98, v98
	s_nop 0
	v_add_f32_e32 v98, 1.0, v98
	v_rcp_f32_e32 v153, v98
	v_mov_b32_e32 v98, v60
	v_pk_mul_f32 v[98:99], v[152:153], v[98:99]
	s_nop 0
	v_mul_f32_e32 v100, v98, v99
	v_and_b32_e32 v99, 0xffff0000, v96
	v_mul_f32_e32 v60, 0xbfb8aa3b, v99
	v_exp_f32_e32 v60, v60
	v_mov_b32_e32 v98, v61
	v_add_f32_e32 v60, 1.0, v60
	v_rcp_f32_e32 v153, v60
	s_nop 0
	v_pk_mul_f32 v[60:61], v[152:153], v[98:99]
	s_nop 0
	v_mul_f32_e32 v60, v60, v61
	v_lshlrev_b32_e32 v61, 16, v97
	v_cvt_pk_bf16_f32 v96, v100, v60
	v_mul_f32_e32 v60, 0xbfb8aa3b, v61
	v_exp_f32_e32 v60, v60
	s_nop 0
	v_add_f32_e32 v60, 1.0, v60
	v_rcp_f32_e32 v153, v60
	v_mov_b32_e32 v60, v62
	v_pk_mul_f32 v[60:61], v[152:153], v[60:61]
	s_nop 0
	v_mul_f32_e32 v62, v60, v61
	v_and_b32_e32 v61, 0xffff0000, v97
	v_mul_f32_e32 v60, 0xbfb8aa3b, v61
	v_exp_f32_e32 v60, v60
	s_nop 0
	v_add_f32_e32 v60, 1.0, v60
	v_rcp_f32_e32 v153, v60
	v_mov_b32_e32 v60, v63
	s_waitcnt vmcnt(14)
	v_lshlrev_b32_e32 v63, 16, v92
	v_pk_mul_f32 v[60:61], v[152:153], v[60:61]
	s_nop 0
	v_mul_f32_e32 v60, v60, v61
	v_cvt_pk_bf16_f32 v97, v62, v60
	v_mul_f32_e32 v62, 0xbfb8aa3b, v63
	v_exp_f32_e32 v62, v62
	v_add_co_u32_e32 v60, vcc, s93, v94
	v_add_f32_e32 v62, 1.0, v62
	v_rcp_f32_e32 v153, v62
	v_mov_b32_e32 v62, v56
	v_addc_co_u32_e32 v61, vcc, 0, v95, vcc
	v_pk_mul_f32 v[62:63], v[152:153], v[62:63]
	ds_write_b64 v187, v[96:97]
	v_mul_f32_e32 v94, v62, v63
	v_and_b32_e32 v63, 0xffff0000, v92
	v_mul_f32_e32 v56, 0xbfb8aa3b, v63
	v_exp_f32_e32 v56, v56
	v_mov_b32_e32 v62, v57
	v_add_f32_e32 v56, 1.0, v56
	v_rcp_f32_e32 v153, v56
	s_nop 0
	v_pk_mul_f32 v[56:57], v[152:153], v[62:63]
	v_lshlrev_b32_e32 v63, 16, v93
	v_mul_f32_e32 v56, v56, v57
	v_mul_f32_e32 v57, 0xbfb8aa3b, v63
	v_exp_f32_e32 v57, v57
	v_mov_b32_e32 v62, v58
	v_cvt_pk_bf16_f32 v56, v94, v56
	v_add_f32_e32 v57, 1.0, v57
	v_rcp_f32_e32 v153, v57
	s_nop 0
	v_pk_mul_f32 v[62:63], v[152:153], v[62:63]
	s_nop 0
	v_mul_f32_e32 v57, v62, v63
	v_and_b32_e32 v63, 0xffff0000, v93
	v_mul_f32_e32 v58, 0xbfb8aa3b, v63
	v_exp_f32_e32 v58, v58
	v_mov_b32_e32 v62, v59
	v_add_f32_e32 v58, 1.0, v58
	v_rcp_f32_e32 v153, v58
	s_nop 0
	v_pk_mul_f32 v[58:59], v[152:153], v[62:63]
	s_nop 0
	v_mul_f32_e32 v58, v58, v59
	v_cvt_pk_bf16_f32 v57, v57, v58
	ds_write_b64 v187, v[56:57] offset:32
	s_waitcnt vmcnt(15)
	v_lshlrev_b32_e32 v57, 16, v90
	v_mul_f32_e32 v56, 0xbfb8aa3b, v57
	v_exp_f32_e32 v56, v56
	s_nop 0
	v_add_f32_e32 v56, 1.0, v56
	v_rcp_f32_e32 v153, v56
	v_mov_b32_e32 v56, v52
	v_pk_mul_f32 v[56:57], v[152:153], v[56:57]
	s_nop 0
	v_mul_f32_e32 v58, v56, v57
	v_and_b32_e32 v57, 0xffff0000, v90
	v_mul_f32_e32 v52, 0xbfb8aa3b, v57
	v_exp_f32_e32 v52, v52
	v_mov_b32_e32 v56, v53
	v_add_f32_e32 v52, 1.0, v52
	v_rcp_f32_e32 v153, v52
	s_nop 0
	v_pk_mul_f32 v[52:53], v[152:153], v[56:57]
	v_lshlrev_b32_e32 v57, 16, v91
	v_mul_f32_e32 v52, v52, v53
	v_mul_f32_e32 v53, 0xbfb8aa3b, v57
	v_exp_f32_e32 v53, v53
	v_mov_b32_e32 v56, v54
	v_cvt_pk_bf16_f32 v52, v58, v52
	v_add_f32_e32 v53, 1.0, v53
	v_rcp_f32_e32 v153, v53
	s_nop 0
	v_pk_mul_f32 v[56:57], v[152:153], v[56:57]
	s_nop 0
	v_mul_f32_e32 v53, v56, v57
	v_and_b32_e32 v57, 0xffff0000, v91
	v_mul_f32_e32 v54, 0xbfb8aa3b, v57
	v_exp_f32_e32 v54, v54
	v_mov_b32_e32 v56, v55
	v_add_f32_e32 v54, 1.0, v54
	v_rcp_f32_e32 v153, v54
	s_nop 0
	v_pk_mul_f32 v[54:55], v[152:153], v[56:57]
	s_nop 0
	v_mul_f32_e32 v54, v54, v55
	v_cvt_pk_bf16_f32 v53, v53, v54
	ds_write_b64 v187, v[52:53] offset:64
	s_waitcnt vmcnt(15)
	v_lshlrev_b32_e32 v53, 16, v88
	v_mul_f32_e32 v52, 0xbfb8aa3b, v53
	v_exp_f32_e32 v52, v52
	s_nop 0
	v_add_f32_e32 v52, 1.0, v52
	v_rcp_f32_e32 v153, v52
	v_mov_b32_e32 v52, v48
	v_pk_mul_f32 v[52:53], v[152:153], v[52:53]
	s_nop 0
	v_mul_f32_e32 v54, v52, v53
	v_and_b32_e32 v53, 0xffff0000, v88
	v_mul_f32_e32 v48, 0xbfb8aa3b, v53
	v_exp_f32_e32 v48, v48
	v_mov_b32_e32 v52, v49
	v_add_f32_e32 v48, 1.0, v48
	v_rcp_f32_e32 v153, v48
	s_nop 0
	v_pk_mul_f32 v[48:49], v[152:153], v[52:53]
	v_lshlrev_b32_e32 v53, 16, v89
	v_mul_f32_e32 v48, v48, v49
	v_mul_f32_e32 v49, 0xbfb8aa3b, v53
	v_exp_f32_e32 v49, v49
	v_mov_b32_e32 v52, v50
	v_cvt_pk_bf16_f32 v48, v54, v48
	v_add_f32_e32 v49, 1.0, v49
	v_rcp_f32_e32 v153, v49
	s_nop 0
	v_pk_mul_f32 v[52:53], v[152:153], v[52:53]
	s_nop 0
	v_mul_f32_e32 v49, v52, v53
	v_and_b32_e32 v53, 0xffff0000, v89
	v_mul_f32_e32 v50, 0xbfb8aa3b, v53
	v_exp_f32_e32 v50, v50
	v_mov_b32_e32 v52, v51
	v_add_f32_e32 v50, 1.0, v50
	v_rcp_f32_e32 v153, v50
	s_nop 0
	v_pk_mul_f32 v[50:51], v[152:153], v[52:53]
	s_nop 0
	v_mul_f32_e32 v50, v50, v51
	v_cvt_pk_bf16_f32 v49, v49, v50
	ds_write_b64 v187, v[48:49] offset:96
	s_waitcnt vmcnt(15)
	v_lshlrev_b32_e32 v49, 16, v86
	v_mul_f32_e32 v48, 0xbfb8aa3b, v49
	v_exp_f32_e32 v48, v48
	s_nop 0
	v_add_f32_e32 v48, 1.0, v48
	v_rcp_f32_e32 v153, v48
	v_mov_b32_e32 v48, v44
	v_pk_mul_f32 v[48:49], v[152:153], v[48:49]
	s_nop 0
	v_mul_f32_e32 v50, v48, v49
	v_and_b32_e32 v49, 0xffff0000, v86
	v_mul_f32_e32 v44, 0xbfb8aa3b, v49
	v_exp_f32_e32 v44, v44
	v_mov_b32_e32 v48, v45
	v_add_f32_e32 v44, 1.0, v44
	v_rcp_f32_e32 v153, v44
	s_nop 0
	v_pk_mul_f32 v[44:45], v[152:153], v[48:49]
	v_lshlrev_b32_e32 v49, 16, v87
	v_mul_f32_e32 v44, v44, v45
	v_mul_f32_e32 v45, 0xbfb8aa3b, v49
	v_exp_f32_e32 v45, v45
	v_mov_b32_e32 v48, v46
	v_cvt_pk_bf16_f32 v44, v50, v44
	v_add_f32_e32 v45, 1.0, v45
	v_rcp_f32_e32 v153, v45
	s_nop 0
	v_pk_mul_f32 v[48:49], v[152:153], v[48:49]
	s_nop 0
	v_mul_f32_e32 v45, v48, v49
	v_and_b32_e32 v49, 0xffff0000, v87
	v_mul_f32_e32 v46, 0xbfb8aa3b, v49
	v_exp_f32_e32 v46, v46
	v_mov_b32_e32 v48, v47
	v_add_f32_e32 v46, 1.0, v46
	v_rcp_f32_e32 v153, v46
	s_nop 0
	v_pk_mul_f32 v[46:47], v[152:153], v[48:49]
	s_nop 0
	v_mul_f32_e32 v46, v46, v47
	v_cvt_pk_bf16_f32 v45, v45, v46
	ds_write_b64 v187, v[44:45] offset:128
	s_waitcnt vmcnt(15)
	v_lshlrev_b32_e32 v45, 16, v84
	v_mul_f32_e32 v44, 0xbfb8aa3b, v45
	v_exp_f32_e32 v44, v44
	s_nop 0
	v_add_f32_e32 v44, 1.0, v44
	v_rcp_f32_e32 v153, v44
	v_mov_b32_e32 v44, v40
	v_pk_mul_f32 v[44:45], v[152:153], v[44:45]
	s_nop 0
	v_mul_f32_e32 v46, v44, v45
	v_and_b32_e32 v45, 0xffff0000, v84
	v_mul_f32_e32 v40, 0xbfb8aa3b, v45
	v_exp_f32_e32 v40, v40
	v_mov_b32_e32 v44, v41
	v_add_f32_e32 v40, 1.0, v40
	v_rcp_f32_e32 v153, v40
	s_nop 0
	v_pk_mul_f32 v[40:41], v[152:153], v[44:45]
	v_lshlrev_b32_e32 v45, 16, v85
	v_mul_f32_e32 v40, v40, v41
	v_mul_f32_e32 v41, 0xbfb8aa3b, v45
	v_exp_f32_e32 v41, v41
	v_mov_b32_e32 v44, v42
	v_cvt_pk_bf16_f32 v40, v46, v40
	v_add_f32_e32 v41, 1.0, v41
	v_rcp_f32_e32 v153, v41
	s_nop 0
	v_pk_mul_f32 v[44:45], v[152:153], v[44:45]
	s_nop 0
	v_mul_f32_e32 v41, v44, v45
	v_and_b32_e32 v45, 0xffff0000, v85
	v_mul_f32_e32 v42, 0xbfb8aa3b, v45
	v_exp_f32_e32 v42, v42
	v_mov_b32_e32 v44, v43
	v_add_f32_e32 v42, 1.0, v42
	v_rcp_f32_e32 v153, v42
	s_nop 0
	v_pk_mul_f32 v[42:43], v[152:153], v[44:45]
	s_nop 0
	v_mul_f32_e32 v42, v42, v43
	v_cvt_pk_bf16_f32 v41, v41, v42
	ds_write_b64 v187, v[40:41] offset:160
	s_waitcnt vmcnt(15)
	v_lshlrev_b32_e32 v41, 16, v82
	v_mul_f32_e32 v40, 0xbfb8aa3b, v41
	v_exp_f32_e32 v40, v40
	s_nop 0
	v_add_f32_e32 v40, 1.0, v40
	v_rcp_f32_e32 v153, v40
	v_mov_b32_e32 v40, v36
	v_pk_mul_f32 v[40:41], v[152:153], v[40:41]
	s_nop 0
	v_mul_f32_e32 v42, v40, v41
	v_and_b32_e32 v41, 0xffff0000, v82
	v_mul_f32_e32 v36, 0xbfb8aa3b, v41
	v_exp_f32_e32 v36, v36
	v_mov_b32_e32 v40, v37
	v_add_f32_e32 v36, 1.0, v36
	v_rcp_f32_e32 v153, v36
	s_nop 0
	v_pk_mul_f32 v[36:37], v[152:153], v[40:41]
	v_lshlrev_b32_e32 v41, 16, v83
	v_mul_f32_e32 v36, v36, v37
	v_mul_f32_e32 v37, 0xbfb8aa3b, v41
	v_exp_f32_e32 v37, v37
	v_mov_b32_e32 v40, v38
	v_cvt_pk_bf16_f32 v36, v42, v36
	v_add_f32_e32 v37, 1.0, v37
	v_rcp_f32_e32 v153, v37
	s_nop 0
	v_pk_mul_f32 v[40:41], v[152:153], v[40:41]
	s_nop 0
	v_mul_f32_e32 v37, v40, v41
	v_and_b32_e32 v41, 0xffff0000, v83
	v_mul_f32_e32 v38, 0xbfb8aa3b, v41
	v_exp_f32_e32 v38, v38
	v_mov_b32_e32 v40, v39
	v_add_f32_e32 v38, 1.0, v38
	v_rcp_f32_e32 v153, v38
	s_nop 0
	v_pk_mul_f32 v[38:39], v[152:153], v[40:41]
	s_nop 0
	v_mul_f32_e32 v38, v38, v39
	v_cvt_pk_bf16_f32 v37, v37, v38
	ds_write_b64 v187, v[36:37] offset:192
	s_waitcnt vmcnt(15)
	v_lshlrev_b32_e32 v37, 16, v80
	v_mul_f32_e32 v36, 0xbfb8aa3b, v37
	v_exp_f32_e32 v36, v36
	s_nop 0
	v_add_f32_e32 v36, 1.0, v36
	v_rcp_f32_e32 v153, v36
	v_mov_b32_e32 v36, v32
	v_pk_mul_f32 v[36:37], v[152:153], v[36:37]
	s_nop 0
	v_mul_f32_e32 v38, v36, v37
	v_and_b32_e32 v37, 0xffff0000, v80
	v_mul_f32_e32 v32, 0xbfb8aa3b, v37
	v_exp_f32_e32 v32, v32
	v_mov_b32_e32 v36, v33
	v_add_f32_e32 v32, 1.0, v32
	v_rcp_f32_e32 v153, v32
	s_nop 0
	v_pk_mul_f32 v[32:33], v[152:153], v[36:37]
	v_lshlrev_b32_e32 v37, 16, v81
	v_mul_f32_e32 v32, v32, v33
	v_mul_f32_e32 v33, 0xbfb8aa3b, v37
	v_exp_f32_e32 v33, v33
	v_mov_b32_e32 v36, v34
	v_cvt_pk_bf16_f32 v32, v38, v32
	v_add_f32_e32 v33, 1.0, v33
	v_rcp_f32_e32 v153, v33
	s_nop 0
	v_pk_mul_f32 v[36:37], v[152:153], v[36:37]
	s_nop 0
	v_mul_f32_e32 v33, v36, v37
	v_and_b32_e32 v37, 0xffff0000, v81
	v_mul_f32_e32 v34, 0xbfb8aa3b, v37
	v_exp_f32_e32 v34, v34
	v_mov_b32_e32 v36, v35
	v_add_f32_e32 v34, 1.0, v34
	v_rcp_f32_e32 v153, v34
	s_nop 0
	v_pk_mul_f32 v[34:35], v[152:153], v[36:37]
	s_nop 0
	v_mul_f32_e32 v34, v34, v35
	v_cvt_pk_bf16_f32 v33, v33, v34
	ds_write_b64 v187, v[32:33] offset:224
	s_waitcnt vmcnt(15)
	v_lshlrev_b32_e32 v33, 16, v78
	v_mul_f32_e32 v32, 0xbfb8aa3b, v33
	v_exp_f32_e32 v32, v32
	s_nop 0
	v_add_f32_e32 v32, 1.0, v32
	v_rcp_f32_e32 v153, v32
	v_mov_b32_e32 v32, v28
	v_pk_mul_f32 v[32:33], v[152:153], v[32:33]
	s_nop 0
	v_mul_f32_e32 v34, v32, v33
	v_and_b32_e32 v33, 0xffff0000, v78
	v_mul_f32_e32 v28, 0xbfb8aa3b, v33
	v_exp_f32_e32 v28, v28
	v_mov_b32_e32 v32, v29
	v_add_f32_e32 v28, 1.0, v28
	v_rcp_f32_e32 v153, v28
	s_nop 0
	v_pk_mul_f32 v[28:29], v[152:153], v[32:33]
	v_lshlrev_b32_e32 v33, 16, v79
	v_mul_f32_e32 v28, v28, v29
	v_mul_f32_e32 v29, 0xbfb8aa3b, v33
	v_exp_f32_e32 v29, v29
	v_mov_b32_e32 v32, v30
	v_cvt_pk_bf16_f32 v28, v34, v28
	v_add_f32_e32 v29, 1.0, v29
	v_rcp_f32_e32 v153, v29
	s_nop 0
	v_pk_mul_f32 v[32:33], v[152:153], v[32:33]
	s_nop 0
	v_mul_f32_e32 v29, v32, v33
	v_and_b32_e32 v33, 0xffff0000, v79
	v_mul_f32_e32 v30, 0xbfb8aa3b, v33
	v_exp_f32_e32 v30, v30
	v_mov_b32_e32 v32, v31
	v_add_f32_e32 v30, 1.0, v30
	v_rcp_f32_e32 v153, v30
	s_nop 0
	v_pk_mul_f32 v[30:31], v[152:153], v[32:33]
	s_nop 0
	v_mul_f32_e32 v30, v30, v31
	v_cvt_pk_bf16_f32 v29, v29, v30
	ds_write_b64 v187, v[28:29] offset:256
	s_waitcnt vmcnt(15)
	v_lshlrev_b32_e32 v29, 16, v76
	v_mul_f32_e32 v28, 0xbfb8aa3b, v29
	v_exp_f32_e32 v28, v28
	s_nop 0
	v_add_f32_e32 v28, 1.0, v28
	v_rcp_f32_e32 v153, v28
	v_mov_b32_e32 v28, v24
	v_pk_mul_f32 v[28:29], v[152:153], v[28:29]
	s_nop 0
	v_mul_f32_e32 v30, v28, v29
	v_and_b32_e32 v29, 0xffff0000, v76
	v_mul_f32_e32 v24, 0xbfb8aa3b, v29
	v_exp_f32_e32 v24, v24
	v_mov_b32_e32 v28, v25
	v_add_f32_e32 v24, 1.0, v24
	v_rcp_f32_e32 v153, v24
	s_nop 0
	v_pk_mul_f32 v[24:25], v[152:153], v[28:29]
	v_lshlrev_b32_e32 v29, 16, v77
	v_mul_f32_e32 v24, v24, v25
	v_mul_f32_e32 v25, 0xbfb8aa3b, v29
	v_exp_f32_e32 v25, v25
	v_mov_b32_e32 v28, v26
	v_cvt_pk_bf16_f32 v24, v30, v24
	v_add_f32_e32 v25, 1.0, v25
	v_rcp_f32_e32 v153, v25
	s_nop 0
	v_pk_mul_f32 v[28:29], v[152:153], v[28:29]
	s_nop 0
	v_mul_f32_e32 v25, v28, v29
	v_and_b32_e32 v29, 0xffff0000, v77
	v_mul_f32_e32 v26, 0xbfb8aa3b, v29
	v_exp_f32_e32 v26, v26
	v_mov_b32_e32 v28, v27
	v_add_f32_e32 v26, 1.0, v26
	v_rcp_f32_e32 v153, v26
	s_nop 0
	v_pk_mul_f32 v[26:27], v[152:153], v[28:29]
	s_nop 0
	v_mul_f32_e32 v26, v26, v27
	v_cvt_pk_bf16_f32 v25, v25, v26
	ds_write_b64 v187, v[24:25] offset:288
	s_waitcnt vmcnt(15)
	v_lshlrev_b32_e32 v25, 16, v74
	v_mul_f32_e32 v24, 0xbfb8aa3b, v25
	v_exp_f32_e32 v24, v24
	s_nop 0
	v_add_f32_e32 v24, 1.0, v24
	v_rcp_f32_e32 v153, v24
	v_mov_b32_e32 v24, v20
	v_pk_mul_f32 v[24:25], v[152:153], v[24:25]
	s_nop 0
	v_mul_f32_e32 v26, v24, v25
	v_and_b32_e32 v25, 0xffff0000, v74
	v_mul_f32_e32 v20, 0xbfb8aa3b, v25
	v_exp_f32_e32 v20, v20
	v_mov_b32_e32 v24, v21
	v_add_f32_e32 v20, 1.0, v20
	v_rcp_f32_e32 v153, v20
	s_nop 0
	v_pk_mul_f32 v[20:21], v[152:153], v[24:25]
	v_lshlrev_b32_e32 v25, 16, v75
	v_mul_f32_e32 v20, v20, v21
	v_mul_f32_e32 v21, 0xbfb8aa3b, v25
	v_exp_f32_e32 v21, v21
	v_mov_b32_e32 v24, v22
	v_cvt_pk_bf16_f32 v20, v26, v20
	v_add_f32_e32 v21, 1.0, v21
	v_rcp_f32_e32 v153, v21
	s_nop 0
	v_pk_mul_f32 v[24:25], v[152:153], v[24:25]
	s_nop 0
	v_mul_f32_e32 v21, v24, v25
	v_and_b32_e32 v25, 0xffff0000, v75
	v_mul_f32_e32 v22, 0xbfb8aa3b, v25
	v_exp_f32_e32 v22, v22
	v_mov_b32_e32 v24, v23
	v_add_f32_e32 v22, 1.0, v22
	v_rcp_f32_e32 v153, v22
	s_nop 0
	v_pk_mul_f32 v[22:23], v[152:153], v[24:25]
	s_nop 0
	v_mul_f32_e32 v22, v22, v23
	v_cvt_pk_bf16_f32 v21, v21, v22
	ds_write_b64 v187, v[20:21] offset:320
	s_waitcnt vmcnt(15)
	v_lshlrev_b32_e32 v21, 16, v72
	v_mul_f32_e32 v20, 0xbfb8aa3b, v21
	v_exp_f32_e32 v20, v20
	s_nop 0
	v_add_f32_e32 v20, 1.0, v20
	v_rcp_f32_e32 v153, v20
	v_mov_b32_e32 v20, v16
	v_pk_mul_f32 v[20:21], v[152:153], v[20:21]
	s_nop 0
	v_mul_f32_e32 v22, v20, v21
	v_and_b32_e32 v21, 0xffff0000, v72
	v_mul_f32_e32 v16, 0xbfb8aa3b, v21
	v_exp_f32_e32 v16, v16
	v_mov_b32_e32 v20, v17
	v_add_f32_e32 v16, 1.0, v16
	v_rcp_f32_e32 v153, v16
	s_nop 0
	v_pk_mul_f32 v[16:17], v[152:153], v[20:21]
	v_lshlrev_b32_e32 v21, 16, v73
	v_mul_f32_e32 v16, v16, v17
	v_mul_f32_e32 v17, 0xbfb8aa3b, v21
	v_exp_f32_e32 v17, v17
	v_mov_b32_e32 v20, v18
	v_cvt_pk_bf16_f32 v16, v22, v16
	v_add_f32_e32 v17, 1.0, v17
	v_rcp_f32_e32 v153, v17
	s_nop 0
	v_pk_mul_f32 v[20:21], v[152:153], v[20:21]
	s_nop 0
	v_mul_f32_e32 v17, v20, v21
	v_and_b32_e32 v21, 0xffff0000, v73
	v_mul_f32_e32 v18, 0xbfb8aa3b, v21
	v_exp_f32_e32 v18, v18
	v_mov_b32_e32 v20, v19
	v_add_f32_e32 v18, 1.0, v18
	v_rcp_f32_e32 v153, v18
	s_nop 0
	v_pk_mul_f32 v[18:19], v[152:153], v[20:21]
	s_nop 0
	v_mul_f32_e32 v18, v18, v19
	v_cvt_pk_bf16_f32 v17, v17, v18
	ds_write_b64 v187, v[16:17] offset:352
	s_waitcnt vmcnt(15)
	v_lshlrev_b32_e32 v17, 16, v70
	v_mul_f32_e32 v16, 0xbfb8aa3b, v17
	v_exp_f32_e32 v16, v16
	s_nop 0
	v_add_f32_e32 v16, 1.0, v16
	v_rcp_f32_e32 v153, v16
	v_mov_b32_e32 v16, v12
	v_pk_mul_f32 v[16:17], v[152:153], v[16:17]
	s_nop 0
	v_mul_f32_e32 v18, v16, v17
	v_and_b32_e32 v17, 0xffff0000, v70
	v_mul_f32_e32 v12, 0xbfb8aa3b, v17
	v_exp_f32_e32 v12, v12
	v_mov_b32_e32 v16, v13
	v_add_f32_e32 v12, 1.0, v12
	v_rcp_f32_e32 v153, v12
	s_nop 0
	v_pk_mul_f32 v[12:13], v[152:153], v[16:17]
	v_lshlrev_b32_e32 v17, 16, v71
	v_mul_f32_e32 v12, v12, v13
	v_mul_f32_e32 v13, 0xbfb8aa3b, v17
	v_exp_f32_e32 v13, v13
	v_mov_b32_e32 v16, v14
	v_cvt_pk_bf16_f32 v12, v18, v12
	v_add_f32_e32 v13, 1.0, v13
	v_rcp_f32_e32 v153, v13
	s_nop 0
	v_pk_mul_f32 v[16:17], v[152:153], v[16:17]
	s_nop 0
	v_mul_f32_e32 v13, v16, v17
	v_and_b32_e32 v17, 0xffff0000, v71
	v_mul_f32_e32 v14, 0xbfb8aa3b, v17
	v_exp_f32_e32 v14, v14
	v_mov_b32_e32 v16, v15
	v_add_f32_e32 v14, 1.0, v14
	v_rcp_f32_e32 v153, v14
	s_nop 0
	v_pk_mul_f32 v[14:15], v[152:153], v[16:17]
	s_nop 0
	v_mul_f32_e32 v14, v14, v15
	v_cvt_pk_bf16_f32 v13, v13, v14
	ds_write_b64 v187, v[12:13] offset:384
	s_waitcnt vmcnt(15)
	v_lshlrev_b32_e32 v13, 16, v68
	v_mul_f32_e32 v12, 0xbfb8aa3b, v13
	v_exp_f32_e32 v12, v12
	s_nop 0
	v_add_f32_e32 v12, 1.0, v12
	v_rcp_f32_e32 v153, v12
	v_mov_b32_e32 v12, v8
	v_pk_mul_f32 v[12:13], v[152:153], v[12:13]
	s_nop 0
	v_mul_f32_e32 v14, v12, v13
	v_and_b32_e32 v13, 0xffff0000, v68
	v_mul_f32_e32 v8, 0xbfb8aa3b, v13
	v_exp_f32_e32 v8, v8
	v_mov_b32_e32 v12, v9
	v_add_f32_e32 v8, 1.0, v8
	v_rcp_f32_e32 v153, v8
	s_nop 0
	v_pk_mul_f32 v[8:9], v[152:153], v[12:13]
	v_lshlrev_b32_e32 v13, 16, v69
	v_mul_f32_e32 v8, v8, v9
	v_mul_f32_e32 v9, 0xbfb8aa3b, v13
	v_exp_f32_e32 v9, v9
	v_mov_b32_e32 v12, v10
	v_cvt_pk_bf16_f32 v8, v14, v8
	v_add_f32_e32 v9, 1.0, v9
	v_rcp_f32_e32 v153, v9
	s_nop 0
	v_pk_mul_f32 v[12:13], v[152:153], v[12:13]
	s_nop 0
	v_mul_f32_e32 v9, v12, v13
	v_and_b32_e32 v13, 0xffff0000, v69
	v_mul_f32_e32 v10, 0xbfb8aa3b, v13
	v_exp_f32_e32 v10, v10
	v_mov_b32_e32 v12, v11
	v_add_f32_e32 v10, 1.0, v10
	v_rcp_f32_e32 v153, v10
	s_nop 0
	v_pk_mul_f32 v[10:11], v[152:153], v[12:13]
	s_nop 0
	v_mul_f32_e32 v10, v10, v11
	v_cvt_pk_bf16_f32 v9, v9, v10
	ds_write_b64 v187, v[8:9] offset:416
	s_waitcnt vmcnt(15)
	v_lshlrev_b32_e32 v9, 16, v66
	v_mul_f32_e32 v8, 0xbfb8aa3b, v9
	v_exp_f32_e32 v8, v8
	s_nop 0
	v_add_f32_e32 v8, 1.0, v8
	v_rcp_f32_e32 v153, v8
	v_mov_b32_e32 v8, v4
	v_pk_mul_f32 v[8:9], v[152:153], v[8:9]
	s_nop 0
	v_mul_f32_e32 v10, v8, v9
	v_and_b32_e32 v9, 0xffff0000, v66
	v_mul_f32_e32 v4, 0xbfb8aa3b, v9
	v_exp_f32_e32 v4, v4
	v_mov_b32_e32 v8, v5
	v_add_f32_e32 v4, 1.0, v4
	v_rcp_f32_e32 v153, v4
	s_nop 0
	v_pk_mul_f32 v[4:5], v[152:153], v[8:9]
	v_lshlrev_b32_e32 v9, 16, v67
	v_mul_f32_e32 v4, v4, v5
	v_mul_f32_e32 v5, 0xbfb8aa3b, v9
	v_exp_f32_e32 v5, v5
	v_mov_b32_e32 v8, v6
	v_cvt_pk_bf16_f32 v4, v10, v4
	v_add_f32_e32 v5, 1.0, v5
	v_rcp_f32_e32 v153, v5
	s_nop 0
	v_pk_mul_f32 v[8:9], v[152:153], v[8:9]
	s_nop 0
	v_mul_f32_e32 v5, v8, v9
	v_and_b32_e32 v9, 0xffff0000, v67
	v_mul_f32_e32 v6, 0xbfb8aa3b, v9
	v_exp_f32_e32 v6, v6
	v_mov_b32_e32 v8, v7
	v_add_f32_e32 v6, 1.0, v6
	v_rcp_f32_e32 v153, v6
	s_nop 0
	v_pk_mul_f32 v[6:7], v[152:153], v[8:9]
	s_nop 0
	v_mul_f32_e32 v6, v6, v7
	v_cvt_pk_bf16_f32 v5, v5, v6
	ds_write_b64 v187, v[4:5] offset:448
	s_waitcnt vmcnt(15)
	v_lshlrev_b32_e32 v5, 16, v64
	v_mul_f32_e32 v4, 0xbfb8aa3b, v5
	v_exp_f32_e32 v4, v4
	s_nop 0
	v_add_f32_e32 v4, 1.0, v4
	v_rcp_f32_e32 v153, v4
	v_mov_b32_e32 v4, v0
	v_pk_mul_f32 v[4:5], v[152:153], v[4:5]
	s_nop 0
	v_mul_f32_e32 v6, v4, v5
	v_and_b32_e32 v5, 0xffff0000, v64
	v_mul_f32_e32 v0, 0xbfb8aa3b, v5
	v_exp_f32_e32 v0, v0
	v_mov_b32_e32 v4, v1
	v_add_f32_e32 v0, 1.0, v0
	v_rcp_f32_e32 v153, v0
	s_nop 0
	v_pk_mul_f32 v[0:1], v[152:153], v[4:5]
	v_lshlrev_b32_e32 v5, 16, v65
	v_mul_f32_e32 v0, v0, v1
	v_mul_f32_e32 v1, 0xbfb8aa3b, v5
	v_exp_f32_e32 v1, v1
	v_mov_b32_e32 v4, v2
	v_cvt_pk_bf16_f32 v0, v6, v0
	v_add_f32_e32 v1, 1.0, v1
	v_rcp_f32_e32 v153, v1
	s_nop 0
	v_pk_mul_f32 v[4:5], v[152:153], v[4:5]
	s_nop 0
	v_mul_f32_e32 v1, v4, v5
	v_and_b32_e32 v5, 0xffff0000, v65
	v_mul_f32_e32 v2, 0xbfb8aa3b, v5
	v_exp_f32_e32 v2, v2
	v_mov_b32_e32 v4, v3
	v_add_f32_e32 v2, 1.0, v2
	v_rcp_f32_e32 v153, v2
	s_nop 0
	v_pk_mul_f32 v[2:3], v[152:153], v[4:5]
	s_nop 0
	v_mul_f32_e32 v2, v2, v3
	v_cvt_pk_bf16_f32 v1, v1, v2
	ds_write_b64 v187, v[0:1] offset:480
	s_waitcnt lgkmcnt(0)
	v_lshl_add_u64 v[192:193], v[60:61], 0, v[188:189]
	ds_read_b128 v[202:205], v201
	ds_read_b128 v[206:209], v201 offset:1088
	ds_read_b128 v[210:213], v201 offset:2176
	ds_read_b128 v[214:217], v201 offset:3264
	ds_read_b128 v[218:221], v201 offset:4352
	ds_read_b128 v[222:225], v201 offset:5440
	ds_read_b128 v[226:229], v201 offset:6528
	ds_read_b128 v[230:233], v201 offset:7616
	s_waitcnt lgkmcnt(7)
	global_store_dwordx4 v[192:193], v[202:205], off
	s_waitcnt lgkmcnt(6)
	v_lshl_add_u64 v[192:193], v[192:193], 0, s[0:1]
	global_store_dwordx4 v[192:193], v[206:209], off
	s_waitcnt lgkmcnt(5)
	v_lshl_add_u64 v[192:193], v[192:193], 0, s[0:1]
	global_store_dwordx4 v[192:193], v[210:213], off
	s_waitcnt lgkmcnt(4)
	v_lshl_add_u64 v[192:193], v[192:193], 0, s[0:1]
	global_store_dwordx4 v[192:193], v[214:217], off
	s_waitcnt lgkmcnt(3)
	v_lshl_add_u64 v[192:193], v[192:193], 0, s[0:1]
	global_store_dwordx4 v[192:193], v[218:221], off
	s_waitcnt lgkmcnt(2)
	v_lshl_add_u64 v[192:193], v[192:193], 0, s[0:1]
	global_store_dwordx4 v[192:193], v[222:225], off
	s_waitcnt lgkmcnt(1)
	v_lshl_add_u64 v[192:193], v[192:193], 0, s[0:1]
	global_store_dwordx4 v[192:193], v[226:229], off
	s_waitcnt lgkmcnt(0)
	v_lshl_add_u64 v[192:193], v[192:193], 0, s[0:1]
	global_store_dwordx4 v[192:193], v[230:233], off
